# waitcnt consolidation: vmcnt(8) and lgkmcnt(0) before each mainloop barrier merged into one s_waitcnt
# baseline (speedup 1.0000x reference)
; #define PG8_STAGE(bufoff, gbase, voff) do { _Pragma("unroll") for (int _i = 0; _i < 2; ++_i) \
;         __builtin_amdgcn_global_load_lds((const unsigned*)((const char*)(gbase) + (voff)[_i]), (LAS unsigned*)(lds + (bufoff) + ldsw + _i * 8192), 16, 0, 0); } while (0)
; #define PG8_LDA(dst, b, h) do { _Pragma("unroll") for (int m = 0; m < 4; ++m) _Pragma("unroll") for (int k = 0; k < 2; ++k) dst[m][k] = *(const LAS bf16x8*)(lds + PG8_SA(b, h) + aoff + m * 2048 + k * 1024); } while (0)
; #define PG8_LDB(dst, b, h) do { _Pragma("unroll") for (int n = 0; n < 2; ++n) _Pragma("unroll") for (int k = 0; k < 2; ++k) dst[n][k] = *(const LAS bf16x8*)(lds + PG8_SB(b, h) + boff + n * 2048 + k * 1024); } while (0)
; #define PG8_MMA(ai, bj, At, Bt) do { __builtin_amdgcn_s_setprio(1); _Pragma("unroll") for (int m = 0; m < 4; ++m) _Pragma("unroll") for (int n = 0; n < 2; ++n) _Pragma("unroll") for (int k = 0; k < 2; ++k) \
;         acc[ai][bj][m][n] = __builtin_amdgcn_mfma_f32_16x16x32_bf16(Bt[n][k], At[m][k], acc[ai][bj][m][n], 0, 0, 0); __builtin_amdgcn_s_setprio(0); } while (0)
; #define PG8_WAIT_V(n) asm volatile("s_waitcnt vmcnt(" #n ")" ::: "memory")
; template <class Epi, bool ALIGN_EPI, bool SP2 = PG8_SP2_DEFAULT>
; __device__ __forceinline__ void gemm_phase(LAS unsigned char* lds, const Gemm g, const StaticOrder& S, const Epi& E) {
;     ...
;         const char* nA = has_next ? PG8_ABASE(nxt) : cA; const char* nB = has_next ? (const char*)g.Bt + (size_t)nxt.pn * tstepB : cB;
;         for (int t = 0; t < nt; t += 2) {
;             const bool last = (t == nt - 2);
;             const char* a1 = cA + (size_t)(t + 1) * kstep;
;             const char* a2 = last ? nA : cA + (size_t)(t + 2) * kstep; const char* b2 = last ? nB : cB + (size_t)(t + 2) * kstep;
;             const char* a3 = a2 + kstep; const char* b3 = b2 + kstep;
;             if constexpr (SP2) {
;             PG8_LDB(B0, 0, 0); PG8_LDB(B1, 0, 1); PG8_SCHED; PG8_LDA(At, 0, 0); PG8_STAGE(PG8_SA(1, 1), a1 + hstepA, voffA);
;             PG8_WAIT_V(8); PG8_WAIT_L(0); PG8_BAR; PG8_MMA(0, 0, At, B0); PG8_MMA(0, 1, At, B1); PG8_BAR; PG8_SCHED;
;             PG8_LDA(At, 0, 1); PG8_STAGE(PG8_SB(0, 0), b2, voffB); PG8_STAGE(PG8_SB(0, 1), b2 + hstepB, voffB); PG8_STAGE(PG8_SA(0, 0), a2, voffA);
;             PG8_WAIT_V(8); PG8_WAIT_L(0); PG8_BAR; PG8_MMA(1, 0, At, B0); PG8_MMA(1, 1, At, B1); PG8_BAR; PG8_SCHED;
.LBB0_250:
	ds_read_b128 v[150:153], v147
	ds_read_b128 v[154:157], v147 offset:1024
	ds_read_b128 v[158:161], v147 offset:2048
	ds_read_b128 v[162:165], v147 offset:3072
	ds_read_b128 v[166:169], v148
	ds_read_b128 v[170:173], v148 offset:1024
	ds_read_b128 v[174:177], v148 offset:2048
	ds_read_b128 v[178:181], v148 offset:3072
	s_add_u32 s20, s18, 0xfff00080
	s_addc_u32 s21, s19, -1
	s_cmp_eq_u32 s44, 60
	s_cselect_b32 s23, s13, s21
	s_cselect_b32 s22, s40, s20
	s_cselect_b32 s21, s11, s43
	s_cselect_b32 s20, s41, s42
	v_lshl_add_u64 v[206:207], s[18:19], 0, v[136:137]
	s_add_i32 m0, s9, 0xc000
	ds_read_b128 v[182:185], v149
	ds_read_b128 v[186:189], v149 offset:1024
	ds_read_b128 v[190:193], v149 offset:2048
	ds_read_b128 v[198:201], v149 offset:3072
	ds_read_b128 v[202:205], v149 offset:4096
	ds_read_b128 v[216:219], v149 offset:5120
	ds_read_b128 v[220:223], v149 offset:6144
	ds_read_b128 v[224:227], v149 offset:7168
	global_load_lds_dwordx4 v[206:207], off
	v_lshl_add_u64 v[206:207], s[18:19], 0, v[138:139]
	s_add_i32 m0, s9, 0xe000
	s_nop 0
	global_load_lds_dwordx4 v[206:207], off
	s_waitcnt vmcnt(8) lgkmcnt(0)
	s_setprio 1
	s_barrier
	v_mfma_f32_16x16x32_bf16 v[124:127], v[150:153], v[182:185], v[124:127]
	v_mfma_f32_16x16x32_bf16 v[120:123], v[158:161], v[182:185], v[120:123]
	v_mfma_f32_16x16x32_bf16 v[116:119], v[150:153], v[190:193], v[116:119]
	v_mfma_f32_16x16x32_bf16 v[112:115], v[158:161], v[190:193], v[112:115]
	v_mfma_f32_16x16x32_bf16 v[100:103], v[150:153], v[202:205], v[100:103]
	v_mfma_f32_16x16x32_bf16 v[96:99], v[158:161], v[202:205], v[96:99]
	v_mfma_f32_16x16x32_bf16 v[84:87], v[150:153], v[220:223], v[84:87]
	v_mfma_f32_16x16x32_bf16 v[80:83], v[158:161], v[220:223], v[80:83]
	v_mfma_f32_16x16x32_bf16 v[124:127], v[154:157], v[186:189], v[124:127]
	v_mfma_f32_16x16x32_bf16 v[120:123], v[162:165], v[186:189], v[120:123]
	v_mfma_f32_16x16x32_bf16 v[116:119], v[154:157], v[198:201], v[116:119]
	v_mfma_f32_16x16x32_bf16 v[112:115], v[162:165], v[198:201], v[112:115]
	v_mfma_f32_16x16x32_bf16 v[100:103], v[154:157], v[216:219], v[100:103]
	v_mfma_f32_16x16x32_bf16 v[96:99], v[162:165], v[216:219], v[96:99]
	v_mfma_f32_16x16x32_bf16 v[84:87], v[154:157], v[224:227], v[84:87]
	v_mfma_f32_16x16x32_bf16 v[80:83], v[162:165], v[224:227], v[80:83]
	v_mfma_f32_16x16x32_bf16 v[108:111], v[166:169], v[182:185], v[108:111]
	v_mfma_f32_16x16x32_bf16 v[104:107], v[174:177], v[182:185], v[104:107]
	v_mfma_f32_16x16x32_bf16 v[92:95], v[166:169], v[190:193], v[92:95]
	v_mfma_f32_16x16x32_bf16 v[88:91], v[174:177], v[190:193], v[88:91]
	v_mfma_f32_16x16x32_bf16 v[76:79], v[166:169], v[202:205], v[76:79]
	v_mfma_f32_16x16x32_bf16 v[72:75], v[174:177], v[202:205], v[72:75]
	v_mfma_f32_16x16x32_bf16 v[68:71], v[166:169], v[220:223], v[68:71]
	v_mfma_f32_16x16x32_bf16 v[64:67], v[174:177], v[220:223], v[64:67]
	v_mfma_f32_16x16x32_bf16 v[108:111], v[170:173], v[186:189], v[108:111]
	v_mfma_f32_16x16x32_bf16 v[104:107], v[178:181], v[186:189], v[104:107]
	v_mfma_f32_16x16x32_bf16 v[92:95], v[170:173], v[198:201], v[92:95]
	v_mfma_f32_16x16x32_bf16 v[88:91], v[178:181], v[198:201], v[88:91]
	v_mfma_f32_16x16x32_bf16 v[76:79], v[170:173], v[216:219], v[76:79]
	v_mfma_f32_16x16x32_bf16 v[72:75], v[178:181], v[216:219], v[72:75]
	v_mfma_f32_16x16x32_bf16 v[68:71], v[170:173], v[224:227], v[68:71]
	v_mfma_f32_16x16x32_bf16 v[64:67], v[178:181], v[224:227], v[64:67]
	s_barrier
	s_setprio 0
	s_add_i32 s45, s36, s24
	v_lshl_add_u64 v[206:207], s[20:21], 0, v[132:133]
	s_mov_b32 m0, s45
	ds_read_b128 v[182:185], v149 offset:16384
	ds_read_b128 v[186:189], v149 offset:17408
	ds_read_b128 v[190:193], v149 offset:18432
	ds_read_b128 v[198:201], v149 offset:19456
	ds_read_b128 v[202:205], v149 offset:20480
	ds_read_b128 v[216:219], v149 offset:21504
	ds_read_b128 v[220:223], v149 offset:22528
	ds_read_b128 v[224:227], v149 offset:23552
	global_load_lds_dwordx4 v[206:207], off
	s_add_i32 m0, s45, 0x2000
	s_add_u32 s46, s20, 0x100000
	v_lshl_add_u64 v[210:211], s[20:21], 0, v[128:129]
	s_addc_u32 s47, s21, 0
	s_add_i32 s45, s37, s24
	global_load_lds_dwordx4 v[210:211], off
	v_lshl_add_u64 v[228:229], s[46:47], 0, v[132:133]
	s_mov_b32 m0, s45
	v_lshl_add_u64 v[230:231], s[22:23], 0, v[130:131]
	global_load_lds_dwordx4 v[228:229], off
	v_lshl_add_u64 v[228:229], s[46:47], 0, v[128:129]
	s_add_i32 m0, s45, 0x2000
	s_nop 0
	global_load_lds_dwordx4 v[228:229], off
	v_lshl_add_u64 v[228:229], s[22:23], 0, v[134:135]
	s_mov_b32 m0, s9
	s_nop 0
	global_load_lds_dwordx4 v[228:229], off
	s_mov_b32 m0, s27
	s_nop 0
	global_load_lds_dwordx4 v[230:231], off
	s_waitcnt vmcnt(8) lgkmcnt(0)
	s_setprio 1
	s_barrier
; #define PG8_STAGE(bufoff, gbase, voff) do { _Pragma("unroll") for (int _i = 0; _i < 2; ++_i) \
;         __builtin_amdgcn_global_load_lds((const unsigned*)((const char*)(gbase) + (voff)[_i]), (LAS unsigned*)(lds + (bufoff) + ldsw + _i * 8192), 16, 0, 0); } while (0)
; #define PG8_LDA(dst, b, h) do { _Pragma("unroll") for (int m = 0; m < 4; ++m) _Pragma("unroll") for (int k = 0; k < 2; ++k) dst[m][k] = *(const LAS bf16x8*)(lds + PG8_SA(b, h) + aoff + m * 2048 + k * 1024); } while (0)
; #define PG8_LDB(dst, b, h) do { _Pragma("unroll") for (int n = 0; n < 2; ++n) _Pragma("unroll") for (int k = 0; k < 2; ++k) dst[n][k] = *(const LAS bf16x8*)(lds + PG8_SB(b, h) + boff + n * 2048 + k * 1024); } while (0)
; #define PG8_MMA(ai, bj, At, Bt) do { __builtin_amdgcn_s_setprio(1); _Pragma("unroll") for (int m = 0; m < 4; ++m) _Pragma("unroll") for (int n = 0; n < 2; ++n) _Pragma("unroll") for (int k = 0; k < 2; ++k) \
;         acc[ai][bj][m][n] = __builtin_amdgcn_mfma_f32_16x16x32_bf16(Bt[n][k], At[m][k], acc[ai][bj][m][n], 0, 0, 0); __builtin_amdgcn_s_setprio(0); } while (0)
; #define PG8_WAIT_V(n) asm volatile("s_waitcnt vmcnt(" #n ")" ::: "memory")
; #define PG8_WAIT_L(n) asm volatile("s_waitcnt lgkmcnt(" #n ")" ::: "memory")
; #define PG8_BAR __builtin_amdgcn_s_barrier()
; #define PG8_SCHED __builtin_amdgcn_sched_barrier(0)
; template <class Epi, bool ALIGN_EPI, bool SP2 = PG8_SP2_DEFAULT>
; __device__ __forceinline__ void gemm_phase(LAS unsigned char* lds, const Gemm g, const StaticOrder& S, const Epi& E) {
;     ...
;             PG8_WAIT_V(8); PG8_WAIT_L(0); PG8_BAR; PG8_MMA(1, 0, At, B0); PG8_MMA(1, 1, At, B1); PG8_BAR; PG8_SCHED;
;             PG8_LDB(B0, 1, 0); PG8_LDB(B1, 1, 1); PG8_SCHED; PG8_LDA(At, 1, 0); PG8_STAGE(PG8_SA(0, 1), a2 + hstepA, voffA);
;             PG8_WAIT_V(8); PG8_WAIT_L(0); PG8_BAR; PG8_MMA(0, 0, At, B0); PG8_MMA(0, 1, At, B1); PG8_BAR; PG8_SCHED;
	v_mfma_f32_16x16x32_bf16 v[60:63], v[150:153], v[182:185], v[60:63]
	v_mfma_f32_16x16x32_bf16 v[56:59], v[158:161], v[182:185], v[56:59]
	v_mfma_f32_16x16x32_bf16 v[52:55], v[150:153], v[190:193], v[52:55]
	v_mfma_f32_16x16x32_bf16 v[48:51], v[158:161], v[190:193], v[48:51]
	v_mfma_f32_16x16x32_bf16 v[36:39], v[150:153], v[202:205], v[36:39]
	v_mfma_f32_16x16x32_bf16 v[32:35], v[158:161], v[202:205], v[32:35]
	v_mfma_f32_16x16x32_bf16 v[20:23], v[150:153], v[220:223], v[20:23]
	v_mfma_f32_16x16x32_bf16 v[16:19], v[158:161], v[220:223], v[16:19]
	v_mfma_f32_16x16x32_bf16 v[60:63], v[154:157], v[186:189], v[60:63]
	v_mfma_f32_16x16x32_bf16 v[56:59], v[162:165], v[186:189], v[56:59]
	v_mfma_f32_16x16x32_bf16 v[52:55], v[154:157], v[198:201], v[52:55]
	v_mfma_f32_16x16x32_bf16 v[48:51], v[162:165], v[198:201], v[48:51]
	v_mfma_f32_16x16x32_bf16 v[36:39], v[154:157], v[216:219], v[36:39]
	v_mfma_f32_16x16x32_bf16 v[32:35], v[162:165], v[216:219], v[32:35]
	v_mfma_f32_16x16x32_bf16 v[20:23], v[154:157], v[224:227], v[20:23]
	v_mfma_f32_16x16x32_bf16 v[16:19], v[162:165], v[224:227], v[16:19]
	v_mfma_f32_16x16x32_bf16 v[44:47], v[166:169], v[182:185], v[44:47]
	v_mfma_f32_16x16x32_bf16 v[40:43], v[174:177], v[182:185], v[40:43]
	v_mfma_f32_16x16x32_bf16 v[28:31], v[166:169], v[190:193], v[28:31]
	v_mfma_f32_16x16x32_bf16 v[24:27], v[174:177], v[190:193], v[24:27]
	v_mfma_f32_16x16x32_bf16 v[12:15], v[166:169], v[202:205], v[12:15]
	v_mfma_f32_16x16x32_bf16 v[8:11], v[174:177], v[202:205], v[8:11]
	v_mfma_f32_16x16x32_bf16 v[4:7], v[166:169], v[220:223], v[4:7]
	v_mfma_f32_16x16x32_bf16 v[0:3], v[174:177], v[220:223], v[0:3]
	v_mfma_f32_16x16x32_bf16 v[44:47], v[170:173], v[186:189], v[44:47]
	v_mfma_f32_16x16x32_bf16 v[40:43], v[178:181], v[186:189], v[40:43]
	v_mfma_f32_16x16x32_bf16 v[28:31], v[170:173], v[198:201], v[28:31]
	v_mfma_f32_16x16x32_bf16 v[24:27], v[178:181], v[198:201], v[24:27]
	v_mfma_f32_16x16x32_bf16 v[12:15], v[170:173], v[216:219], v[12:15]
	v_mfma_f32_16x16x32_bf16 v[8:11], v[178:181], v[216:219], v[8:11]
	v_mfma_f32_16x16x32_bf16 v[4:7], v[170:173], v[224:227], v[4:7]
	v_mfma_f32_16x16x32_bf16 v[0:3], v[178:181], v[224:227], v[0:3]
	s_barrier
	s_setprio 0
	s_add_i32 s45, 0, 0x18000
	s_add_i32 s46, 0, 0x1c000
	v_add_u32_e32 v162, s45, v145
	v_add_u32_e32 v178, s46, v145
	ds_read_b128 v[150:153], v162
	ds_read_b128 v[154:157], v162 offset:1024
	ds_read_b128 v[158:161], v162 offset:2048
	ds_read_b128 v[162:165], v162 offset:3072
	ds_read_b128 v[166:169], v178
	ds_read_b128 v[170:173], v178 offset:1024
	ds_read_b128 v[174:177], v178 offset:2048
	ds_read_b128 v[178:181], v178 offset:3072
	s_add_u32 s22, s22, 0x100000
	s_addc_u32 s23, s23, 0
	s_mov_b32 m0, s28
	v_lshl_add_u64 v[232:233], s[22:23], 0, v[134:135]
	ds_read_b128 v[182:185], v149 offset:32768
	ds_read_b128 v[186:189], v149 offset:33792
	ds_read_b128 v[190:193], v149 offset:34816
	ds_read_b128 v[198:201], v149 offset:35840
	ds_read_b128 v[202:205], v149 offset:36864
	ds_read_b128 v[216:219], v149 offset:37888
	ds_read_b128 v[220:223], v149 offset:38912
	ds_read_b128 v[224:227], v149 offset:39936
	global_load_lds_dwordx4 v[232:233], off
	v_lshl_add_u64 v[232:233], s[22:23], 0, v[130:131]
	s_mov_b32 m0, s29
	s_nop 0
	global_load_lds_dwordx4 v[232:233], off
	s_waitcnt vmcnt(8) lgkmcnt(0)
	s_setprio 1
	s_barrier
	v_mfma_f32_16x16x32_bf16 v[124:127], v[150:153], v[182:185], v[124:127]
	v_mfma_f32_16x16x32_bf16 v[120:123], v[158:161], v[182:185], v[120:123]
	v_mfma_f32_16x16x32_bf16 v[116:119], v[150:153], v[190:193], v[116:119]
	v_mfma_f32_16x16x32_bf16 v[112:115], v[158:161], v[190:193], v[112:115]
	v_mfma_f32_16x16x32_bf16 v[100:103], v[150:153], v[202:205], v[100:103]
	v_mfma_f32_16x16x32_bf16 v[96:99], v[158:161], v[202:205], v[96:99]
	v_mfma_f32_16x16x32_bf16 v[84:87], v[150:153], v[220:223], v[84:87]
	v_mfma_f32_16x16x32_bf16 v[80:83], v[158:161], v[220:223], v[80:83]
	v_mfma_f32_16x16x32_bf16 v[124:127], v[154:157], v[186:189], v[124:127]
	v_mfma_f32_16x16x32_bf16 v[120:123], v[162:165], v[186:189], v[120:123]
	v_mfma_f32_16x16x32_bf16 v[116:119], v[154:157], v[198:201], v[116:119]
	v_mfma_f32_16x16x32_bf16 v[112:115], v[162:165], v[198:201], v[112:115]
	v_mfma_f32_16x16x32_bf16 v[100:103], v[154:157], v[216:219], v[100:103]
	v_mfma_f32_16x16x32_bf16 v[96:99], v[162:165], v[216:219], v[96:99]
	v_mfma_f32_16x16x32_bf16 v[84:87], v[154:157], v[224:227], v[84:87]
	v_mfma_f32_16x16x32_bf16 v[80:83], v[162:165], v[224:227], v[80:83]
	v_mfma_f32_16x16x32_bf16 v[108:111], v[166:169], v[182:185], v[108:111]
	v_mfma_f32_16x16x32_bf16 v[104:107], v[174:177], v[182:185], v[104:107]
	v_mfma_f32_16x16x32_bf16 v[92:95], v[166:169], v[190:193], v[92:95]
	v_mfma_f32_16x16x32_bf16 v[88:91], v[174:177], v[190:193], v[88:91]
	v_mfma_f32_16x16x32_bf16 v[76:79], v[166:169], v[202:205], v[76:79]
	v_mfma_f32_16x16x32_bf16 v[72:75], v[174:177], v[202:205], v[72:75]
	v_mfma_f32_16x16x32_bf16 v[68:71], v[166:169], v[220:223], v[68:71]
	v_mfma_f32_16x16x32_bf16 v[64:67], v[174:177], v[220:223], v[64:67]
	v_mfma_f32_16x16x32_bf16 v[108:111], v[170:173], v[186:189], v[108:111]
	v_mfma_f32_16x16x32_bf16 v[104:107], v[178:181], v[186:189], v[104:107]
	v_mfma_f32_16x16x32_bf16 v[92:95], v[170:173], v[198:201], v[92:95]
	v_mfma_f32_16x16x32_bf16 v[88:91], v[178:181], v[198:201], v[88:91]
	v_mfma_f32_16x16x32_bf16 v[76:79], v[170:173], v[216:219], v[76:79]
	v_mfma_f32_16x16x32_bf16 v[72:75], v[178:181], v[216:219], v[72:75]
	v_mfma_f32_16x16x32_bf16 v[68:71], v[170:173], v[224:227], v[68:71]
	v_mfma_f32_16x16x32_bf16 v[64:67], v[178:181], v[224:227], v[64:67]
	s_barrier
; #define PG8_STAGE(bufoff, gbase, voff) do { _Pragma("unroll") for (int _i = 0; _i < 2; ++_i) \
;         __builtin_amdgcn_global_load_lds((const unsigned*)((const char*)(gbase) + (voff)[_i]), (LAS unsigned*)(lds + (bufoff) + ldsw + _i * 8192), 16, 0, 0); } while (0)
; #define PG8_LDA(dst, b, h) do { _Pragma("unroll") for (int m = 0; m < 4; ++m) _Pragma("unroll") for (int k = 0; k < 2; ++k) dst[m][k] = *(const LAS bf16x8*)(lds + PG8_SA(b, h) + aoff + m * 2048 + k * 1024); } while (0)
; #define PG8_MMA(ai, bj, At, Bt) do { __builtin_amdgcn_s_setprio(1); _Pragma("unroll") for (int m = 0; m < 4; ++m) _Pragma("unroll") for (int n = 0; n < 2; ++n) _Pragma("unroll") for (int k = 0; k < 2; ++k) \
;         acc[ai][bj][m][n] = __builtin_amdgcn_mfma_f32_16x16x32_bf16(Bt[n][k], At[m][k], acc[ai][bj][m][n], 0, 0, 0); __builtin_amdgcn_s_setprio(0); } while (0)
; #define PG8_WAIT_V(n) asm volatile("s_waitcnt vmcnt(" #n ")" ::: "memory")
; #define PG8_WAIT_L(n) asm volatile("s_waitcnt lgkmcnt(" #n ")" ::: "memory")
; #define PG8_BAR __builtin_amdgcn_s_barrier()
; #define PG8_SCHED __builtin_amdgcn_sched_barrier(0)
; template <class Epi, bool ALIGN_EPI, bool SP2 = PG8_SP2_DEFAULT>
; __device__ __forceinline__ void gemm_phase(LAS unsigned char* lds, const Gemm g, const StaticOrder& S, const Epi& E) {
;     ...
;             PG8_LDA(At, 1, 1); PG8_STAGE(PG8_SB(1, 0), b3, voffB); PG8_STAGE(PG8_SB(1, 1), b3 + hstepB, voffB); PG8_STAGE(PG8_SA(1, 0), a3, voffA);
;             PG8_WAIT_V(8); PG8_WAIT_L(0); PG8_BAR; PG8_MMA(1, 0, At, B0); PG8_MMA(1, 1, At, B1); PG8_BAR; PG8_SCHED;
;     ...
;         if constexpr (ALIGN_EPI) { if (wr == 0) PG8_BAR; }
	s_setprio 0
	s_add_i32 s22, s45, s24
	v_lshl_add_u64 v[206:207], v[206:207], 0, s[4:5]
	s_mov_b32 m0, s22
	ds_read_b128 v[182:185], v149 offset:49152
	ds_read_b128 v[186:189], v149 offset:50176
	ds_read_b128 v[190:193], v149 offset:51200
	ds_read_b128 v[198:201], v149 offset:52224
	ds_read_b128 v[202:205], v149 offset:53248
	ds_read_b128 v[216:219], v149 offset:54272
	ds_read_b128 v[220:223], v149 offset:55296
	ds_read_b128 v[224:227], v149 offset:56320
	global_load_lds_dwordx4 v[206:207], off
	s_add_i32 m0, s22, 0x2000
	s_add_u32 s20, s20, 0x100080
	v_lshl_add_u64 v[206:207], v[210:211], 0, s[4:5]
	s_addc_u32 s21, s21, 0
	s_add_i32 s22, s46, s24
	global_load_lds_dwordx4 v[206:207], off
	v_lshl_add_u64 v[206:207], s[20:21], 0, v[132:133]
	s_mov_b32 m0, s22
	s_nop 0
	global_load_lds_dwordx4 v[206:207], off
	v_lshl_add_u64 v[206:207], s[20:21], 0, v[128:129]
	s_add_i32 m0, s22, 0x2000
	s_nop 0
	global_load_lds_dwordx4 v[206:207], off
	v_lshl_add_u64 v[206:207], v[228:229], 0, s[4:5]
	s_mov_b32 m0, s33
	s_nop 0
	global_load_lds_dwordx4 v[206:207], off
	v_lshl_add_u64 v[206:207], v[230:231], 0, s[4:5]
	s_mov_b32 m0, s34
	s_nop 0
	global_load_lds_dwordx4 v[206:207], off
	s_waitcnt vmcnt(8) lgkmcnt(0)
	s_setprio 1
	s_barrier
	v_mfma_f32_16x16x32_bf16 v[60:63], v[150:153], v[182:185], v[60:63]
	v_mfma_f32_16x16x32_bf16 v[56:59], v[158:161], v[182:185], v[56:59]
	v_mfma_f32_16x16x32_bf16 v[52:55], v[150:153], v[190:193], v[52:55]
	v_mfma_f32_16x16x32_bf16 v[48:51], v[158:161], v[190:193], v[48:51]
	v_mfma_f32_16x16x32_bf16 v[36:39], v[150:153], v[202:205], v[36:39]
	v_mfma_f32_16x16x32_bf16 v[32:35], v[158:161], v[202:205], v[32:35]
	v_mfma_f32_16x16x32_bf16 v[20:23], v[150:153], v[220:223], v[20:23]
	v_mfma_f32_16x16x32_bf16 v[16:19], v[158:161], v[220:223], v[16:19]
	v_mfma_f32_16x16x32_bf16 v[60:63], v[154:157], v[186:189], v[60:63]
	v_mfma_f32_16x16x32_bf16 v[56:59], v[162:165], v[186:189], v[56:59]
	v_mfma_f32_16x16x32_bf16 v[52:55], v[154:157], v[198:201], v[52:55]
	v_mfma_f32_16x16x32_bf16 v[48:51], v[162:165], v[198:201], v[48:51]
	v_mfma_f32_16x16x32_bf16 v[36:39], v[154:157], v[216:219], v[36:39]
	v_mfma_f32_16x16x32_bf16 v[32:35], v[162:165], v[216:219], v[32:35]
	v_mfma_f32_16x16x32_bf16 v[20:23], v[154:157], v[224:227], v[20:23]
	v_mfma_f32_16x16x32_bf16 v[16:19], v[162:165], v[224:227], v[16:19]
	v_mfma_f32_16x16x32_bf16 v[44:47], v[166:169], v[182:185], v[44:47]
	v_mfma_f32_16x16x32_bf16 v[40:43], v[174:177], v[182:185], v[40:43]
	v_mfma_f32_16x16x32_bf16 v[28:31], v[166:169], v[190:193], v[28:31]
	v_mfma_f32_16x16x32_bf16 v[24:27], v[174:177], v[190:193], v[24:27]
	v_mfma_f32_16x16x32_bf16 v[12:15], v[166:169], v[202:205], v[12:15]
	v_mfma_f32_16x16x32_bf16 v[8:11], v[174:177], v[202:205], v[8:11]
	v_mfma_f32_16x16x32_bf16 v[4:7], v[166:169], v[220:223], v[4:7]
	v_mfma_f32_16x16x32_bf16 v[0:3], v[174:177], v[220:223], v[0:3]
	v_mfma_f32_16x16x32_bf16 v[44:47], v[170:173], v[186:189], v[44:47]
	v_mfma_f32_16x16x32_bf16 v[40:43], v[178:181], v[186:189], v[40:43]
	v_mfma_f32_16x16x32_bf16 v[28:31], v[170:173], v[198:201], v[28:31]
	v_mfma_f32_16x16x32_bf16 v[24:27], v[178:181], v[198:201], v[24:27]
	v_mfma_f32_16x16x32_bf16 v[12:15], v[170:173], v[216:219], v[12:15]
	v_mfma_f32_16x16x32_bf16 v[8:11], v[178:181], v[216:219], v[8:11]
	v_mfma_f32_16x16x32_bf16 v[4:7], v[170:173], v[224:227], v[4:7]
	v_mfma_f32_16x16x32_bf16 v[0:3], v[178:181], v[224:227], v[0:3]
	s_barrier
	s_setprio 0
	s_add_i32 s44, s44, 2
	s_add_u32 s18, s18, 0x100
	s_addc_u32 s19, s19, 0
	s_add_u32 s42, s42, 0x100
	s_addc_u32 s43, s43, 0
	s_cmp_gt_u32 s44, 61
	s_cbranch_scc0 .LBB0_250
	s_and_b64 vcc, exec, s[6:7]
	s_cbranch_vccz .LBB0_253
	s_barrier

; #define PG8_STAGE(bufoff, gbase, voff) do { _Pragma("unroll") for (int _i = 0; _i < 2; ++_i) \
;         __builtin_amdgcn_global_load_lds((const unsigned*)((const char*)(gbase) + (voff)[_i]), (LAS unsigned*)(lds + (bufoff) + ldsw + _i * 8192), 16, 0, 0); } while (0)
; #define PG8_LDA(dst, b, h) do { _Pragma("unroll") for (int m = 0; m < 4; ++m) _Pragma("unroll") for (int k = 0; k < 2; ++k) dst[m][k] = *(const LAS bf16x8*)(lds + PG8_SA(b, h) + aoff + m * 2048 + k * 1024); } while (0)
; #define PG8_LDB(dst, b, h) do { _Pragma("unroll") for (int n = 0; n < 2; ++n) _Pragma("unroll") for (int k = 0; k < 2; ++k) dst[n][k] = *(const LAS bf16x8*)(lds + PG8_SB(b, h) + boff + n * 2048 + k * 1024); } while (0)
; #define PG8_MMA(ai, bj, At, Bt) do { __builtin_amdgcn_s_setprio(1); _Pragma("unroll") for (int m = 0; m < 4; ++m) _Pragma("unroll") for (int n = 0; n < 2; ++n) _Pragma("unroll") for (int k = 0; k < 2; ++k) \
;         acc[ai][bj][m][n] = __builtin_amdgcn_mfma_f32_16x16x32_bf16(Bt[n][k], At[m][k], acc[ai][bj][m][n], 0, 0, 0); __builtin_amdgcn_s_setprio(0); } while (0)
; #define PG8_WAIT_V(n) asm volatile("s_waitcnt vmcnt(" #n ")" ::: "memory")
; template <class Epi, bool ALIGN_EPI, bool SP2 = PG8_SP2_DEFAULT>
; __device__ __forceinline__ void gemm_phase(LAS unsigned char* lds, const Gemm g, const StaticOrder& S, const Epi& E) {
;     ...
;         const char* nA = has_next ? PG8_ABASE(nxt) : cA; const char* nB = has_next ? (const char*)g.Bt + (size_t)nxt.pn * tstepB : cB;
;         for (int t = 0; t < nt; t += 2) {
;             const bool last = (t == nt - 2);
;             const char* a1 = cA + (size_t)(t + 1) * kstep;
;             const char* a2 = last ? nA : cA + (size_t)(t + 2) * kstep; const char* b2 = last ? nB : cB + (size_t)(t + 2) * kstep;
;             const char* a3 = a2 + kstep; const char* b3 = b2 + kstep;
;             if constexpr (SP2) {
;             PG8_LDB(B0, 0, 0); PG8_LDB(B1, 0, 1); PG8_SCHED; PG8_LDA(At, 0, 0); PG8_STAGE(PG8_SA(1, 1), a1 + hstepA, voffA);
;             PG8_WAIT_V(8); PG8_WAIT_L(0); PG8_BAR; PG8_MMA(0, 0, At, B0); PG8_MMA(0, 1, At, B1); PG8_BAR; PG8_SCHED;
;             PG8_LDA(At, 0, 1); PG8_STAGE(PG8_SB(0, 0), b2, voffB); PG8_STAGE(PG8_SB(0, 1), b2 + hstepB, voffB); PG8_STAGE(PG8_SA(0, 0), a2, voffA);
;             PG8_WAIT_V(8); PG8_WAIT_L(0); PG8_BAR; PG8_MMA(1, 0, At, B0); PG8_MMA(1, 1, At, B1); PG8_BAR; PG8_SCHED;
.LBB0_428:
	ds_read_b128 v[128:131], v165
	ds_read_b128 v[132:135], v165 offset:1024
	ds_read_b128 v[136:139], v165 offset:2048
	ds_read_b128 v[140:143], v165 offset:3072
	ds_read_b128 v[168:171], v166
	ds_read_b128 v[172:175], v166 offset:1024
	ds_read_b128 v[176:179], v166 offset:2048
	ds_read_b128 v[180:183], v166 offset:3072
	s_add_u32 s24, s22, 0xfffe0080
	s_addc_u32 s25, s23, -1
	s_cmp_eq_u32 s51, 4
	s_cselect_b32 s27, s15, s25
	s_cselect_b32 s26, s47, s24
	s_cselect_b32 s25, s13, s50
	s_cselect_b32 s24, s48, s49
	v_lshl_add_u64 v[160:161], s[22:23], 0, v[152:153]
	s_add_i32 m0, s21, 0xc000
	ds_read_b128 v[184:187], v167
	ds_read_b128 v[188:191], v167 offset:1024
	ds_read_b128 v[198:201], v167 offset:2048
	ds_read_b128 v[202:205], v167 offset:3072
	ds_read_b128 v[216:219], v167 offset:4096
	ds_read_b128 v[220:223], v167 offset:5120
	ds_read_b128 v[224:227], v167 offset:6144
	ds_read_b128 v[228:231], v167 offset:7168
	global_load_lds_dwordx4 v[160:161], off
	v_lshl_add_u64 v[160:161], s[22:23], 0, v[154:155]
	s_add_i32 m0, s21, 0xe000
	s_nop 0
	global_load_lds_dwordx4 v[160:161], off
	s_waitcnt vmcnt(8) lgkmcnt(0)
	s_setprio 1
	s_barrier
	v_mfma_f32_16x16x32_bf16 v[124:127], v[128:131], v[184:187], v[124:127]
	v_mfma_f32_16x16x32_bf16 v[120:123], v[136:139], v[184:187], v[120:123]
	v_mfma_f32_16x16x32_bf16 v[116:119], v[128:131], v[198:201], v[116:119]
	v_mfma_f32_16x16x32_bf16 v[112:115], v[136:139], v[198:201], v[112:115]
	v_mfma_f32_16x16x32_bf16 v[108:111], v[128:131], v[216:219], v[108:111]
	v_mfma_f32_16x16x32_bf16 v[100:103], v[136:139], v[216:219], v[100:103]
	v_mfma_f32_16x16x32_bf16 v[80:83], v[128:131], v[224:227], v[80:83]
	v_mfma_f32_16x16x32_bf16 v[72:75], v[136:139], v[224:227], v[72:75]
	v_mfma_f32_16x16x32_bf16 v[124:127], v[132:135], v[188:191], v[124:127]
	v_mfma_f32_16x16x32_bf16 v[120:123], v[140:143], v[188:191], v[120:123]
	v_mfma_f32_16x16x32_bf16 v[116:119], v[132:135], v[202:205], v[116:119]
	v_mfma_f32_16x16x32_bf16 v[112:115], v[140:143], v[202:205], v[112:115]
	v_mfma_f32_16x16x32_bf16 v[108:111], v[132:135], v[220:223], v[108:111]
	v_mfma_f32_16x16x32_bf16 v[100:103], v[140:143], v[220:223], v[100:103]
	v_mfma_f32_16x16x32_bf16 v[80:83], v[132:135], v[228:231], v[80:83]
	v_mfma_f32_16x16x32_bf16 v[72:75], v[140:143], v[228:231], v[72:75]
	v_mfma_f32_16x16x32_bf16 v[104:107], v[168:171], v[184:187], v[104:107]
	v_mfma_f32_16x16x32_bf16 v[96:99], v[176:179], v[184:187], v[96:99]
	v_mfma_f32_16x16x32_bf16 v[92:95], v[168:171], v[198:201], v[92:95]
	v_mfma_f32_16x16x32_bf16 v[88:91], v[176:179], v[198:201], v[88:91]
	v_mfma_f32_16x16x32_bf16 v[84:87], v[168:171], v[216:219], v[84:87]
	v_mfma_f32_16x16x32_bf16 v[76:79], v[176:179], v[216:219], v[76:79]
	v_mfma_f32_16x16x32_bf16 v[68:71], v[168:171], v[224:227], v[68:71]
	v_mfma_f32_16x16x32_bf16 v[64:67], v[176:179], v[224:227], v[64:67]
	v_mfma_f32_16x16x32_bf16 v[104:107], v[172:175], v[188:191], v[104:107]
	v_mfma_f32_16x16x32_bf16 v[96:99], v[180:183], v[188:191], v[96:99]
	v_mfma_f32_16x16x32_bf16 v[92:95], v[172:175], v[202:205], v[92:95]
	v_mfma_f32_16x16x32_bf16 v[88:91], v[180:183], v[202:205], v[88:91]
	v_mfma_f32_16x16x32_bf16 v[84:87], v[172:175], v[220:223], v[84:87]
	v_mfma_f32_16x16x32_bf16 v[76:79], v[180:183], v[220:223], v[76:79]
	v_mfma_f32_16x16x32_bf16 v[68:71], v[172:175], v[228:231], v[68:71]
	v_mfma_f32_16x16x32_bf16 v[64:67], v[180:183], v[228:231], v[64:67]
	s_barrier
	s_setprio 0
	s_add_i32 s52, s40, s29
	v_lshl_add_u64 v[160:161], s[24:25], 0, v[146:147]
	s_mov_b32 m0, s52
	ds_read_b128 v[184:187], v167 offset:16384
	ds_read_b128 v[188:191], v167 offset:17408
	ds_read_b128 v[198:201], v167 offset:18432
	ds_read_b128 v[202:205], v167 offset:19456
	ds_read_b128 v[216:219], v167 offset:20480
	ds_read_b128 v[220:223], v167 offset:21504
	ds_read_b128 v[224:227], v167 offset:22528
	ds_read_b128 v[228:231], v167 offset:23552
	global_load_lds_dwordx4 v[160:161], off
	s_add_i32 m0, s52, 0x2000
	s_add_u32 s52, s24, 0x20000
	v_lshl_add_u64 v[192:193], s[24:25], 0, v[150:151]
	s_addc_u32 s53, s25, 0
	s_add_i32 s54, s41, s29
	global_load_lds_dwordx4 v[192:193], off
	v_lshl_add_u64 v[206:207], s[52:53], 0, v[146:147]
	s_mov_b32 m0, s54
	v_lshl_add_u64 v[210:211], s[26:27], 0, v[148:149]
	global_load_lds_dwordx4 v[206:207], off
	v_lshl_add_u64 v[206:207], s[52:53], 0, v[150:151]
	s_add_i32 m0, s54, 0x2000
	s_nop 0
	global_load_lds_dwordx4 v[206:207], off
	v_lshl_add_u64 v[206:207], s[26:27], 0, v[144:145]
	s_mov_b32 m0, s21
	s_nop 0
	global_load_lds_dwordx4 v[206:207], off
	s_mov_b32 m0, s30
	s_nop 0
	global_load_lds_dwordx4 v[210:211], off
	s_waitcnt vmcnt(8) lgkmcnt(0)
	s_setprio 1
	s_barrier
; #define PG8_STAGE(bufoff, gbase, voff) do { _Pragma("unroll") for (int _i = 0; _i < 2; ++_i) \
;         __builtin_amdgcn_global_load_lds((const unsigned*)((const char*)(gbase) + (voff)[_i]), (LAS unsigned*)(lds + (bufoff) + ldsw + _i * 8192), 16, 0, 0); } while (0)
; #define PG8_LDA(dst, b, h) do { _Pragma("unroll") for (int m = 0; m < 4; ++m) _Pragma("unroll") for (int k = 0; k < 2; ++k) dst[m][k] = *(const LAS bf16x8*)(lds + PG8_SA(b, h) + aoff + m * 2048 + k * 1024); } while (0)
; #define PG8_LDB(dst, b, h) do { _Pragma("unroll") for (int n = 0; n < 2; ++n) _Pragma("unroll") for (int k = 0; k < 2; ++k) dst[n][k] = *(const LAS bf16x8*)(lds + PG8_SB(b, h) + boff + n * 2048 + k * 1024); } while (0)
; #define PG8_MMA(ai, bj, At, Bt) do { __builtin_amdgcn_s_setprio(1); _Pragma("unroll") for (int m = 0; m < 4; ++m) _Pragma("unroll") for (int n = 0; n < 2; ++n) _Pragma("unroll") for (int k = 0; k < 2; ++k) \
;         acc[ai][bj][m][n] = __builtin_amdgcn_mfma_f32_16x16x32_bf16(Bt[n][k], At[m][k], acc[ai][bj][m][n], 0, 0, 0); __builtin_amdgcn_s_setprio(0); } while (0)
; #define PG8_WAIT_V(n) asm volatile("s_waitcnt vmcnt(" #n ")" ::: "memory")
; #define PG8_WAIT_L(n) asm volatile("s_waitcnt lgkmcnt(" #n ")" ::: "memory")
; #define PG8_BAR __builtin_amdgcn_s_barrier()
; #define PG8_SCHED __builtin_amdgcn_sched_barrier(0)
; template <class Epi, bool ALIGN_EPI, bool SP2 = PG8_SP2_DEFAULT>
; __device__ __forceinline__ void gemm_phase(LAS unsigned char* lds, const Gemm g, const StaticOrder& S, const Epi& E) {
;     ...
;             PG8_WAIT_V(8); PG8_WAIT_L(0); PG8_BAR; PG8_MMA(1, 0, At, B0); PG8_MMA(1, 1, At, B1); PG8_BAR; PG8_SCHED;
;             PG8_LDB(B0, 1, 0); PG8_LDB(B1, 1, 1); PG8_SCHED; PG8_LDA(At, 1, 0); PG8_STAGE(PG8_SA(0, 1), a2 + hstepA, voffA);
;             PG8_WAIT_V(8); PG8_WAIT_L(0); PG8_BAR; PG8_MMA(0, 0, At, B0); PG8_MMA(0, 1, At, B1); PG8_BAR; PG8_SCHED;
	v_mfma_f32_16x16x32_bf16 v[60:63], v[128:131], v[184:187], v[60:63]
	v_mfma_f32_16x16x32_bf16 v[56:59], v[136:139], v[184:187], v[56:59]
	v_mfma_f32_16x16x32_bf16 v[52:55], v[128:131], v[198:201], v[52:55]
	v_mfma_f32_16x16x32_bf16 v[44:47], v[136:139], v[198:201], v[44:47]
	v_mfma_f32_16x16x32_bf16 v[36:39], v[128:131], v[216:219], v[36:39]
	v_mfma_f32_16x16x32_bf16 v[28:31], v[136:139], v[216:219], v[28:31]
	v_mfma_f32_16x16x32_bf16 v[20:23], v[128:131], v[224:227], v[20:23]
	v_mfma_f32_16x16x32_bf16 v[12:15], v[136:139], v[224:227], v[12:15]
	v_mfma_f32_16x16x32_bf16 v[60:63], v[132:135], v[188:191], v[60:63]
	v_mfma_f32_16x16x32_bf16 v[56:59], v[140:143], v[188:191], v[56:59]
	v_mfma_f32_16x16x32_bf16 v[52:55], v[132:135], v[202:205], v[52:55]
	v_mfma_f32_16x16x32_bf16 v[44:47], v[140:143], v[202:205], v[44:47]
	v_mfma_f32_16x16x32_bf16 v[36:39], v[132:135], v[220:223], v[36:39]
	v_mfma_f32_16x16x32_bf16 v[28:31], v[140:143], v[220:223], v[28:31]
	v_mfma_f32_16x16x32_bf16 v[20:23], v[132:135], v[228:231], v[20:23]
	v_mfma_f32_16x16x32_bf16 v[12:15], v[140:143], v[228:231], v[12:15]
	v_mfma_f32_16x16x32_bf16 v[48:51], v[168:171], v[184:187], v[48:51]
	v_mfma_f32_16x16x32_bf16 v[40:43], v[176:179], v[184:187], v[40:43]
	v_mfma_f32_16x16x32_bf16 v[32:35], v[168:171], v[198:201], v[32:35]
	v_mfma_f32_16x16x32_bf16 v[24:27], v[176:179], v[198:201], v[24:27]
	v_mfma_f32_16x16x32_bf16 v[16:19], v[168:171], v[216:219], v[16:19]
	v_mfma_f32_16x16x32_bf16 v[8:11], v[176:179], v[216:219], v[8:11]
	v_mfma_f32_16x16x32_bf16 v[4:7], v[168:171], v[224:227], v[4:7]
	v_mfma_f32_16x16x32_bf16 v[0:3], v[176:179], v[224:227], v[0:3]
	v_mfma_f32_16x16x32_bf16 v[48:51], v[172:175], v[188:191], v[48:51]
	v_mfma_f32_16x16x32_bf16 v[40:43], v[180:183], v[188:191], v[40:43]
	v_mfma_f32_16x16x32_bf16 v[32:35], v[172:175], v[202:205], v[32:35]
	v_mfma_f32_16x16x32_bf16 v[24:27], v[180:183], v[202:205], v[24:27]
	v_mfma_f32_16x16x32_bf16 v[16:19], v[172:175], v[220:223], v[16:19]
	v_mfma_f32_16x16x32_bf16 v[8:11], v[180:183], v[220:223], v[8:11]
	v_mfma_f32_16x16x32_bf16 v[4:7], v[172:175], v[228:231], v[4:7]
	v_mfma_f32_16x16x32_bf16 v[0:3], v[180:183], v[228:231], v[0:3]
	s_barrier
	s_setprio 0
	s_add_i32 s52, 0, 0x18000
	s_add_i32 s53, 0, 0x1c000
	v_add_u32_e32 v140, s52, v163
	v_add_u32_e32 v180, s53, v163
	ds_read_b128 v[128:131], v140
	ds_read_b128 v[132:135], v140 offset:1024
	ds_read_b128 v[136:139], v140 offset:2048
	ds_read_b128 v[140:143], v140 offset:3072
	ds_read_b128 v[168:171], v180
	ds_read_b128 v[172:175], v180 offset:1024
	ds_read_b128 v[176:179], v180 offset:2048
	ds_read_b128 v[180:183], v180 offset:3072
	s_add_u32 s26, s26, 0x20000
	s_addc_u32 s27, s27, 0
	s_mov_b32 m0, s31
	v_lshl_add_u64 v[232:233], s[26:27], 0, v[144:145]
	ds_read_b128 v[184:187], v167 offset:32768
	ds_read_b128 v[188:191], v167 offset:33792
	ds_read_b128 v[198:201], v167 offset:34816
	ds_read_b128 v[202:205], v167 offset:35840
	ds_read_b128 v[216:219], v167 offset:36864
	ds_read_b128 v[220:223], v167 offset:37888
	ds_read_b128 v[224:227], v167 offset:38912
	ds_read_b128 v[228:231], v167 offset:39936
	global_load_lds_dwordx4 v[232:233], off
	v_lshl_add_u64 v[232:233], s[26:27], 0, v[148:149]
	s_mov_b32 m0, s34
	s_nop 0
	global_load_lds_dwordx4 v[232:233], off
	s_waitcnt vmcnt(8) lgkmcnt(0)
	s_setprio 1
	s_barrier
	v_mfma_f32_16x16x32_bf16 v[124:127], v[128:131], v[184:187], v[124:127]
	v_mfma_f32_16x16x32_bf16 v[120:123], v[136:139], v[184:187], v[120:123]
	v_mfma_f32_16x16x32_bf16 v[116:119], v[128:131], v[198:201], v[116:119]
	v_mfma_f32_16x16x32_bf16 v[112:115], v[136:139], v[198:201], v[112:115]
	v_mfma_f32_16x16x32_bf16 v[108:111], v[128:131], v[216:219], v[108:111]
	v_mfma_f32_16x16x32_bf16 v[100:103], v[136:139], v[216:219], v[100:103]
	v_mfma_f32_16x16x32_bf16 v[80:83], v[128:131], v[224:227], v[80:83]
	v_mfma_f32_16x16x32_bf16 v[72:75], v[136:139], v[224:227], v[72:75]
	v_mfma_f32_16x16x32_bf16 v[124:127], v[132:135], v[188:191], v[124:127]
	v_mfma_f32_16x16x32_bf16 v[120:123], v[140:143], v[188:191], v[120:123]
	v_mfma_f32_16x16x32_bf16 v[116:119], v[132:135], v[202:205], v[116:119]
	v_mfma_f32_16x16x32_bf16 v[112:115], v[140:143], v[202:205], v[112:115]
	v_mfma_f32_16x16x32_bf16 v[108:111], v[132:135], v[220:223], v[108:111]
	v_mfma_f32_16x16x32_bf16 v[100:103], v[140:143], v[220:223], v[100:103]
	v_mfma_f32_16x16x32_bf16 v[80:83], v[132:135], v[228:231], v[80:83]
	v_mfma_f32_16x16x32_bf16 v[72:75], v[140:143], v[228:231], v[72:75]
	v_mfma_f32_16x16x32_bf16 v[104:107], v[168:171], v[184:187], v[104:107]
	v_mfma_f32_16x16x32_bf16 v[96:99], v[176:179], v[184:187], v[96:99]
	v_mfma_f32_16x16x32_bf16 v[92:95], v[168:171], v[198:201], v[92:95]
	v_mfma_f32_16x16x32_bf16 v[88:91], v[176:179], v[198:201], v[88:91]
	v_mfma_f32_16x16x32_bf16 v[84:87], v[168:171], v[216:219], v[84:87]
	v_mfma_f32_16x16x32_bf16 v[76:79], v[176:179], v[216:219], v[76:79]
	v_mfma_f32_16x16x32_bf16 v[68:71], v[168:171], v[224:227], v[68:71]
	v_mfma_f32_16x16x32_bf16 v[64:67], v[176:179], v[224:227], v[64:67]
	v_mfma_f32_16x16x32_bf16 v[104:107], v[172:175], v[188:191], v[104:107]
	v_mfma_f32_16x16x32_bf16 v[96:99], v[180:183], v[188:191], v[96:99]
	v_mfma_f32_16x16x32_bf16 v[92:95], v[172:175], v[202:205], v[92:95]
	v_mfma_f32_16x16x32_bf16 v[88:91], v[180:183], v[202:205], v[88:91]
	v_mfma_f32_16x16x32_bf16 v[84:87], v[172:175], v[220:223], v[84:87]
	v_mfma_f32_16x16x32_bf16 v[76:79], v[180:183], v[220:223], v[76:79]
	v_mfma_f32_16x16x32_bf16 v[68:71], v[172:175], v[228:231], v[68:71]
	v_mfma_f32_16x16x32_bf16 v[64:67], v[180:183], v[228:231], v[64:67]
	s_barrier
; #define PG8_STAGE(bufoff, gbase, voff) do { _Pragma("unroll") for (int _i = 0; _i < 2; ++_i) \
;         __builtin_amdgcn_global_load_lds((const unsigned*)((const char*)(gbase) + (voff)[_i]), (LAS unsigned*)(lds + (bufoff) + ldsw + _i * 8192), 16, 0, 0); } while (0)
; #define PG8_LDA(dst, b, h) do { _Pragma("unroll") for (int m = 0; m < 4; ++m) _Pragma("unroll") for (int k = 0; k < 2; ++k) dst[m][k] = *(const LAS bf16x8*)(lds + PG8_SA(b, h) + aoff + m * 2048 + k * 1024); } while (0)
; #define PG8_MMA(ai, bj, At, Bt) do { __builtin_amdgcn_s_setprio(1); _Pragma("unroll") for (int m = 0; m < 4; ++m) _Pragma("unroll") for (int n = 0; n < 2; ++n) _Pragma("unroll") for (int k = 0; k < 2; ++k) \
;         acc[ai][bj][m][n] = __builtin_amdgcn_mfma_f32_16x16x32_bf16(Bt[n][k], At[m][k], acc[ai][bj][m][n], 0, 0, 0); __builtin_amdgcn_s_setprio(0); } while (0)
; #define PG8_WAIT_V(n) asm volatile("s_waitcnt vmcnt(" #n ")" ::: "memory")
; #define PG8_WAIT_L(n) asm volatile("s_waitcnt lgkmcnt(" #n ")" ::: "memory")
; #define PG8_BAR __builtin_amdgcn_s_barrier()
; #define PG8_SCHED __builtin_amdgcn_sched_barrier(0)
; template <class Epi, bool ALIGN_EPI, bool SP2 = PG8_SP2_DEFAULT>
; __device__ __forceinline__ void gemm_phase(LAS unsigned char* lds, const Gemm g, const StaticOrder& S, const Epi& E) {
;     ...
;             PG8_LDA(At, 1, 1); PG8_STAGE(PG8_SB(1, 0), b3, voffB); PG8_STAGE(PG8_SB(1, 1), b3 + hstepB, voffB); PG8_STAGE(PG8_SA(1, 0), a3, voffA);
;             PG8_WAIT_V(8); PG8_WAIT_L(0); PG8_BAR; PG8_MMA(1, 0, At, B0); PG8_MMA(1, 1, At, B1); PG8_BAR; PG8_SCHED;
;     ...
;         if constexpr (ALIGN_EPI) { if (wr == 0) PG8_BAR; }
	s_setprio 0
	s_add_i32 s26, s52, s29
	v_lshl_add_u64 v[160:161], v[160:161], 0, s[4:5]
	s_mov_b32 m0, s26
	ds_read_b128 v[184:187], v167 offset:49152
	ds_read_b128 v[188:191], v167 offset:50176
	ds_read_b128 v[198:201], v167 offset:51200
	ds_read_b128 v[202:205], v167 offset:52224
	ds_read_b128 v[216:219], v167 offset:53248
	ds_read_b128 v[220:223], v167 offset:54272
	ds_read_b128 v[224:227], v167 offset:55296
	ds_read_b128 v[228:231], v167 offset:56320
	global_load_lds_dwordx4 v[160:161], off
	s_add_i32 m0, s26, 0x2000
	s_add_u32 s24, s24, 0x20080
	v_lshl_add_u64 v[160:161], v[192:193], 0, s[4:5]
	s_addc_u32 s25, s25, 0
	s_add_i32 s26, s53, s29
	global_load_lds_dwordx4 v[160:161], off
	v_lshl_add_u64 v[160:161], s[24:25], 0, v[146:147]
	s_mov_b32 m0, s26
	s_nop 0
	global_load_lds_dwordx4 v[160:161], off
	v_lshl_add_u64 v[160:161], s[24:25], 0, v[150:151]
	s_add_i32 m0, s26, 0x2000
	s_nop 0
	global_load_lds_dwordx4 v[160:161], off
	v_lshl_add_u64 v[160:161], v[206:207], 0, s[4:5]
	s_mov_b32 m0, s36
	s_nop 0
	global_load_lds_dwordx4 v[160:161], off
	v_lshl_add_u64 v[160:161], v[210:211], 0, s[4:5]
	s_mov_b32 m0, s37
	s_nop 0
	global_load_lds_dwordx4 v[160:161], off
	s_waitcnt vmcnt(8) lgkmcnt(0)
	s_setprio 1
	s_barrier
	v_mfma_f32_16x16x32_bf16 v[60:63], v[128:131], v[184:187], v[60:63]
	v_mfma_f32_16x16x32_bf16 v[56:59], v[136:139], v[184:187], v[56:59]
	v_mfma_f32_16x16x32_bf16 v[52:55], v[128:131], v[198:201], v[52:55]
	v_mfma_f32_16x16x32_bf16 v[44:47], v[136:139], v[198:201], v[44:47]
	v_mfma_f32_16x16x32_bf16 v[36:39], v[128:131], v[216:219], v[36:39]
	v_mfma_f32_16x16x32_bf16 v[28:31], v[136:139], v[216:219], v[28:31]
	v_mfma_f32_16x16x32_bf16 v[20:23], v[128:131], v[224:227], v[20:23]
	v_mfma_f32_16x16x32_bf16 v[12:15], v[136:139], v[224:227], v[12:15]
	v_mfma_f32_16x16x32_bf16 v[60:63], v[132:135], v[188:191], v[60:63]
	v_mfma_f32_16x16x32_bf16 v[56:59], v[140:143], v[188:191], v[56:59]
	v_mfma_f32_16x16x32_bf16 v[52:55], v[132:135], v[202:205], v[52:55]
	v_mfma_f32_16x16x32_bf16 v[44:47], v[140:143], v[202:205], v[44:47]
	v_mfma_f32_16x16x32_bf16 v[36:39], v[132:135], v[220:223], v[36:39]
	v_mfma_f32_16x16x32_bf16 v[28:31], v[140:143], v[220:223], v[28:31]
	v_mfma_f32_16x16x32_bf16 v[20:23], v[132:135], v[228:231], v[20:23]
	v_mfma_f32_16x16x32_bf16 v[12:15], v[140:143], v[228:231], v[12:15]
	v_mfma_f32_16x16x32_bf16 v[48:51], v[168:171], v[184:187], v[48:51]
	v_mfma_f32_16x16x32_bf16 v[40:43], v[176:179], v[184:187], v[40:43]
	v_mfma_f32_16x16x32_bf16 v[32:35], v[168:171], v[198:201], v[32:35]
	v_mfma_f32_16x16x32_bf16 v[24:27], v[176:179], v[198:201], v[24:27]
	v_mfma_f32_16x16x32_bf16 v[16:19], v[168:171], v[216:219], v[16:19]
	v_mfma_f32_16x16x32_bf16 v[8:11], v[176:179], v[216:219], v[8:11]
	v_mfma_f32_16x16x32_bf16 v[4:7], v[168:171], v[224:227], v[4:7]
	v_mfma_f32_16x16x32_bf16 v[0:3], v[176:179], v[224:227], v[0:3]
	v_mfma_f32_16x16x32_bf16 v[48:51], v[172:175], v[188:191], v[48:51]
	v_mfma_f32_16x16x32_bf16 v[40:43], v[180:183], v[188:191], v[40:43]
	v_mfma_f32_16x16x32_bf16 v[32:35], v[172:175], v[202:205], v[32:35]
	v_mfma_f32_16x16x32_bf16 v[24:27], v[180:183], v[202:205], v[24:27]
	v_mfma_f32_16x16x32_bf16 v[16:19], v[172:175], v[220:223], v[16:19]
	v_mfma_f32_16x16x32_bf16 v[8:11], v[180:183], v[220:223], v[8:11]
	v_mfma_f32_16x16x32_bf16 v[4:7], v[172:175], v[228:231], v[4:7]
	v_mfma_f32_16x16x32_bf16 v[0:3], v[180:183], v[228:231], v[0:3]
	s_barrier
	s_setprio 0
	s_add_i32 s51, s51, 2
	s_add_u32 s22, s22, 0x100
	s_addc_u32 s23, s23, 0
	s_add_u32 s49, s49, 0x100
	s_addc_u32 s50, s50, 0
	s_cmp_gt_u32 s51, 5
	s_cbranch_scc0 .LBB0_428
	s_and_b64 vcc, exec, s[6:7]
	s_cbranch_vccz .LBB0_431
	s_barrier

; #define PG8_STAGE(bufoff, gbase, voff) do { _Pragma("unroll") for (int _i = 0; _i < 2; ++_i) \
;         __builtin_amdgcn_global_load_lds((const unsigned*)((const char*)(gbase) + (voff)[_i]), (LAS unsigned*)(lds + (bufoff) + ldsw + _i * 8192), 16, 0, 0); } while (0)
; #define PG8_LDA(dst, b, h) do { _Pragma("unroll") for (int m = 0; m < 4; ++m) _Pragma("unroll") for (int k = 0; k < 2; ++k) dst[m][k] = *(const LAS bf16x8*)(lds + PG8_SA(b, h) + aoff + m * 2048 + k * 1024); } while (0)
; #define PG8_LDB(dst, b, h) do { _Pragma("unroll") for (int n = 0; n < 2; ++n) _Pragma("unroll") for (int k = 0; k < 2; ++k) dst[n][k] = *(const LAS bf16x8*)(lds + PG8_SB(b, h) + boff + n * 2048 + k * 1024); } while (0)
; #define PG8_MMA(ai, bj, At, Bt) do { __builtin_amdgcn_s_setprio(1); _Pragma("unroll") for (int m = 0; m < 4; ++m) _Pragma("unroll") for (int n = 0; n < 2; ++n) _Pragma("unroll") for (int k = 0; k < 2; ++k) \
;         acc[ai][bj][m][n] = __builtin_amdgcn_mfma_f32_16x16x32_bf16(Bt[n][k], At[m][k], acc[ai][bj][m][n], 0, 0, 0); __builtin_amdgcn_s_setprio(0); } while (0)
; #define PG8_WAIT_V(n) asm volatile("s_waitcnt vmcnt(" #n ")" ::: "memory")
; template <class Epi, bool ALIGN_EPI, bool SP2 = PG8_SP2_DEFAULT>
; __device__ __forceinline__ void gemm_phase(LAS unsigned char* lds, const Gemm g, const StaticOrder& S, const Epi& E) {
;     ...
;         const char* nA = has_next ? PG8_ABASE(nxt) : cA; const char* nB = has_next ? (const char*)g.Bt + (size_t)nxt.pn * tstepB : cB;
;         for (int t = 0; t < nt; t += 2) {
;             const bool last = (t == nt - 2);
;             const char* a1 = cA + (size_t)(t + 1) * kstep;
;             const char* a2 = last ? nA : cA + (size_t)(t + 2) * kstep; const char* b2 = last ? nB : cB + (size_t)(t + 2) * kstep;
;             const char* a3 = a2 + kstep; const char* b3 = b2 + kstep;
;             if constexpr (SP2) {
;             PG8_LDB(B0, 0, 0); PG8_LDB(B1, 0, 1); PG8_SCHED; PG8_LDA(At, 0, 0); PG8_STAGE(PG8_SA(1, 1), a1 + hstepA, voffA);
;             PG8_WAIT_V(8); PG8_WAIT_L(0); PG8_BAR; PG8_MMA(0, 0, At, B0); PG8_MMA(0, 1, At, B1); PG8_BAR; PG8_SCHED;
;             PG8_LDA(At, 0, 1); PG8_STAGE(PG8_SB(0, 0), b2, voffB); PG8_STAGE(PG8_SB(0, 1), b2 + hstepB, voffB); PG8_STAGE(PG8_SA(0, 0), a2, voffA);
;             PG8_WAIT_V(8); PG8_WAIT_L(0); PG8_BAR; PG8_MMA(1, 0, At, B0); PG8_MMA(1, 1, At, B1); PG8_BAR; PG8_SCHED;
.LBB0_506:
	ds_read_b128 v[144:147], v151
	ds_read_b128 v[156:159], v151 offset:1024
	ds_read_b128 v[160:163], v151 offset:2048
	ds_read_b128 v[164:167], v151 offset:3072
	ds_read_b128 v[168:171], v152
	ds_read_b128 v[172:175], v152 offset:1024
	ds_read_b128 v[176:179], v152 offset:2048
	ds_read_b128 v[180:183], v152 offset:3072
	s_add_u32 s28, s26, 0xfff00080
	s_addc_u32 s29, s27, -1
	s_cmp_eq_u32 s50, 60
	s_cselect_b32 s31, s19, s29
	s_cselect_b32 s30, s25, s28
	s_cselect_b32 s29, s3, s49
	s_cselect_b32 s28, s47, s48
	v_lshl_add_u64 v[192:193], s[26:27], 0, v[136:137]
	s_add_i32 m0, s34, 0xc000
	ds_read_b128 v[184:187], v153
	ds_read_b128 v[188:191], v153 offset:1024
	ds_read_b128 v[198:201], v153 offset:2048
	ds_read_b128 v[202:205], v153 offset:3072
	ds_read_b128 v[216:219], v153 offset:4096
	ds_read_b128 v[220:223], v153 offset:5120
	ds_read_b128 v[224:227], v153 offset:6144
	ds_read_b128 v[228:231], v153 offset:7168
	global_load_lds_dwordx4 v[192:193], off
	v_lshl_add_u64 v[192:193], s[26:27], 0, v[138:139]
	s_add_i32 m0, s34, 0xe000
	s_nop 0
	global_load_lds_dwordx4 v[192:193], off
	s_waitcnt vmcnt(8) lgkmcnt(0)
	s_setprio 1
	s_barrier
	v_mfma_f32_16x16x32_bf16 v[124:127], v[144:147], v[184:187], v[124:127]
	v_mfma_f32_16x16x32_bf16 v[120:123], v[160:163], v[184:187], v[120:123]
	v_mfma_f32_16x16x32_bf16 v[108:111], v[144:147], v[198:201], v[108:111]
	v_mfma_f32_16x16x32_bf16 v[104:107], v[160:163], v[198:201], v[104:107]
	v_mfma_f32_16x16x32_bf16 v[92:95], v[144:147], v[216:219], v[92:95]
	v_mfma_f32_16x16x32_bf16 v[88:91], v[160:163], v[216:219], v[88:91]
	v_mfma_f32_16x16x32_bf16 v[76:79], v[144:147], v[224:227], v[76:79]
	v_mfma_f32_16x16x32_bf16 v[72:75], v[160:163], v[224:227], v[72:75]
	v_mfma_f32_16x16x32_bf16 v[124:127], v[156:159], v[188:191], v[124:127]
	v_mfma_f32_16x16x32_bf16 v[120:123], v[164:167], v[188:191], v[120:123]
	v_mfma_f32_16x16x32_bf16 v[108:111], v[156:159], v[202:205], v[108:111]
	v_mfma_f32_16x16x32_bf16 v[104:107], v[164:167], v[202:205], v[104:107]
	v_mfma_f32_16x16x32_bf16 v[92:95], v[156:159], v[220:223], v[92:95]
	v_mfma_f32_16x16x32_bf16 v[88:91], v[164:167], v[220:223], v[88:91]
	v_mfma_f32_16x16x32_bf16 v[76:79], v[156:159], v[228:231], v[76:79]
	v_mfma_f32_16x16x32_bf16 v[72:75], v[164:167], v[228:231], v[72:75]
	v_mfma_f32_16x16x32_bf16 v[116:119], v[168:171], v[184:187], v[116:119]
	v_mfma_f32_16x16x32_bf16 v[112:115], v[176:179], v[184:187], v[112:115]
	v_mfma_f32_16x16x32_bf16 v[100:103], v[168:171], v[198:201], v[100:103]
	v_mfma_f32_16x16x32_bf16 v[96:99], v[176:179], v[198:201], v[96:99]
	v_mfma_f32_16x16x32_bf16 v[84:87], v[168:171], v[216:219], v[84:87]
	v_mfma_f32_16x16x32_bf16 v[80:83], v[176:179], v[216:219], v[80:83]
	v_mfma_f32_16x16x32_bf16 v[68:71], v[168:171], v[224:227], v[68:71]
	v_mfma_f32_16x16x32_bf16 v[64:67], v[176:179], v[224:227], v[64:67]
	v_mfma_f32_16x16x32_bf16 v[116:119], v[172:175], v[188:191], v[116:119]
	v_mfma_f32_16x16x32_bf16 v[112:115], v[180:183], v[188:191], v[112:115]
	v_mfma_f32_16x16x32_bf16 v[100:103], v[172:175], v[202:205], v[100:103]
	v_mfma_f32_16x16x32_bf16 v[96:99], v[180:183], v[202:205], v[96:99]
	v_mfma_f32_16x16x32_bf16 v[84:87], v[172:175], v[220:223], v[84:87]
	v_mfma_f32_16x16x32_bf16 v[80:83], v[180:183], v[220:223], v[80:83]
	v_mfma_f32_16x16x32_bf16 v[68:71], v[172:175], v[228:231], v[68:71]
	v_mfma_f32_16x16x32_bf16 v[64:67], v[180:183], v[228:231], v[64:67]
	s_barrier
	s_setprio 0
	s_add_i32 s51, s44, s33
	v_lshl_add_u64 v[192:193], s[28:29], 0, v[130:131]
	s_mov_b32 m0, s51
	ds_read_b128 v[184:187], v153 offset:16384
	ds_read_b128 v[188:191], v153 offset:17408
	ds_read_b128 v[198:201], v153 offset:18432
	ds_read_b128 v[202:205], v153 offset:19456
	ds_read_b128 v[216:219], v153 offset:20480
	ds_read_b128 v[220:223], v153 offset:21504
	ds_read_b128 v[224:227], v153 offset:22528
	ds_read_b128 v[228:231], v153 offset:23552
	global_load_lds_dwordx4 v[192:193], off
	s_add_i32 m0, s51, 0x2000
	s_add_u32 s52, s28, 0x100000
	v_lshl_add_u64 v[206:207], s[28:29], 0, v[134:135]
	s_addc_u32 s53, s29, 0
	s_add_i32 s51, s45, s33
	global_load_lds_dwordx4 v[206:207], off
	v_lshl_add_u64 v[210:211], s[52:53], 0, v[130:131]
	s_mov_b32 m0, s51
	v_lshl_add_u64 v[232:233], s[30:31], 0, v[132:133]
	global_load_lds_dwordx4 v[210:211], off
	v_lshl_add_u64 v[210:211], s[52:53], 0, v[134:135]
	s_add_i32 m0, s51, 0x2000
	s_nop 0
	global_load_lds_dwordx4 v[210:211], off
	v_lshl_add_u64 v[210:211], s[30:31], 0, v[128:129]
	s_mov_b32 m0, s34
	s_nop 0
	global_load_lds_dwordx4 v[210:211], off
	s_mov_b32 m0, s35
	s_nop 0
	global_load_lds_dwordx4 v[232:233], off
	s_waitcnt vmcnt(8) lgkmcnt(0)
	s_setprio 1
	s_barrier
; #define PG8_STAGE(bufoff, gbase, voff) do { _Pragma("unroll") for (int _i = 0; _i < 2; ++_i) \
;         __builtin_amdgcn_global_load_lds((const unsigned*)((const char*)(gbase) + (voff)[_i]), (LAS unsigned*)(lds + (bufoff) + ldsw + _i * 8192), 16, 0, 0); } while (0)
; #define PG8_LDA(dst, b, h) do { _Pragma("unroll") for (int m = 0; m < 4; ++m) _Pragma("unroll") for (int k = 0; k < 2; ++k) dst[m][k] = *(const LAS bf16x8*)(lds + PG8_SA(b, h) + aoff + m * 2048 + k * 1024); } while (0)
; #define PG8_LDB(dst, b, h) do { _Pragma("unroll") for (int n = 0; n < 2; ++n) _Pragma("unroll") for (int k = 0; k < 2; ++k) dst[n][k] = *(const LAS bf16x8*)(lds + PG8_SB(b, h) + boff + n * 2048 + k * 1024); } while (0)
; #define PG8_MMA(ai, bj, At, Bt) do { __builtin_amdgcn_s_setprio(1); _Pragma("unroll") for (int m = 0; m < 4; ++m) _Pragma("unroll") for (int n = 0; n < 2; ++n) _Pragma("unroll") for (int k = 0; k < 2; ++k) \
;         acc[ai][bj][m][n] = __builtin_amdgcn_mfma_f32_16x16x32_bf16(Bt[n][k], At[m][k], acc[ai][bj][m][n], 0, 0, 0); __builtin_amdgcn_s_setprio(0); } while (0)
; #define PG8_WAIT_V(n) asm volatile("s_waitcnt vmcnt(" #n ")" ::: "memory")
; #define PG8_WAIT_L(n) asm volatile("s_waitcnt lgkmcnt(" #n ")" ::: "memory")
; #define PG8_BAR __builtin_amdgcn_s_barrier()
; #define PG8_SCHED __builtin_amdgcn_sched_barrier(0)
; template <class Epi, bool ALIGN_EPI, bool SP2 = PG8_SP2_DEFAULT>
; __device__ __forceinline__ void gemm_phase(LAS unsigned char* lds, const Gemm g, const StaticOrder& S, const Epi& E) {
;     ...
;             PG8_WAIT_V(8); PG8_WAIT_L(0); PG8_BAR; PG8_MMA(1, 0, At, B0); PG8_MMA(1, 1, At, B1); PG8_BAR; PG8_SCHED;
;             PG8_LDB(B0, 1, 0); PG8_LDB(B1, 1, 1); PG8_SCHED; PG8_LDA(At, 1, 0); PG8_STAGE(PG8_SA(0, 1), a2 + hstepA, voffA);
;             PG8_WAIT_V(8); PG8_WAIT_L(0); PG8_BAR; PG8_MMA(0, 0, At, B0); PG8_MMA(0, 1, At, B1); PG8_BAR; PG8_SCHED;
	v_mfma_f32_16x16x32_bf16 v[60:63], v[144:147], v[184:187], v[60:63]
	v_mfma_f32_16x16x32_bf16 v[56:59], v[160:163], v[184:187], v[56:59]
	v_mfma_f32_16x16x32_bf16 v[44:47], v[144:147], v[198:201], v[44:47]
	v_mfma_f32_16x16x32_bf16 v[40:43], v[160:163], v[198:201], v[40:43]
	v_mfma_f32_16x16x32_bf16 v[28:31], v[144:147], v[216:219], v[28:31]
	v_mfma_f32_16x16x32_bf16 v[24:27], v[160:163], v[216:219], v[24:27]
	v_mfma_f32_16x16x32_bf16 v[12:15], v[144:147], v[224:227], v[12:15]
	v_mfma_f32_16x16x32_bf16 v[8:11], v[160:163], v[224:227], v[8:11]
	v_mfma_f32_16x16x32_bf16 v[60:63], v[156:159], v[188:191], v[60:63]
	v_mfma_f32_16x16x32_bf16 v[56:59], v[164:167], v[188:191], v[56:59]
	v_mfma_f32_16x16x32_bf16 v[44:47], v[156:159], v[202:205], v[44:47]
	v_mfma_f32_16x16x32_bf16 v[40:43], v[164:167], v[202:205], v[40:43]
	v_mfma_f32_16x16x32_bf16 v[28:31], v[156:159], v[220:223], v[28:31]
	v_mfma_f32_16x16x32_bf16 v[24:27], v[164:167], v[220:223], v[24:27]
	v_mfma_f32_16x16x32_bf16 v[12:15], v[156:159], v[228:231], v[12:15]
	v_mfma_f32_16x16x32_bf16 v[8:11], v[164:167], v[228:231], v[8:11]
	v_mfma_f32_16x16x32_bf16 v[52:55], v[168:171], v[184:187], v[52:55]
	v_mfma_f32_16x16x32_bf16 v[48:51], v[176:179], v[184:187], v[48:51]
	v_mfma_f32_16x16x32_bf16 v[36:39], v[168:171], v[198:201], v[36:39]
	v_mfma_f32_16x16x32_bf16 v[32:35], v[176:179], v[198:201], v[32:35]
	v_mfma_f32_16x16x32_bf16 v[20:23], v[168:171], v[216:219], v[20:23]
	v_mfma_f32_16x16x32_bf16 v[16:19], v[176:179], v[216:219], v[16:19]
	v_mfma_f32_16x16x32_bf16 v[4:7], v[168:171], v[224:227], v[4:7]
	v_mfma_f32_16x16x32_bf16 v[0:3], v[176:179], v[224:227], v[0:3]
	v_mfma_f32_16x16x32_bf16 v[52:55], v[172:175], v[188:191], v[52:55]
	v_mfma_f32_16x16x32_bf16 v[48:51], v[180:183], v[188:191], v[48:51]
	v_mfma_f32_16x16x32_bf16 v[36:39], v[172:175], v[202:205], v[36:39]
	v_mfma_f32_16x16x32_bf16 v[32:35], v[180:183], v[202:205], v[32:35]
	v_mfma_f32_16x16x32_bf16 v[20:23], v[172:175], v[220:223], v[20:23]
	v_mfma_f32_16x16x32_bf16 v[16:19], v[180:183], v[220:223], v[16:19]
	v_mfma_f32_16x16x32_bf16 v[4:7], v[172:175], v[228:231], v[4:7]
	v_mfma_f32_16x16x32_bf16 v[0:3], v[180:183], v[228:231], v[0:3]
	s_barrier
	s_setprio 0
	s_add_i32 s51, 0, 0x18000
	v_add_u32_e32 v155, s51, v149
	s_add_i32 s52, 0, 0x1c000
	ds_read_b128 v[144:147], v155
	ds_read_b128 v[156:159], v155 offset:1024
	ds_read_b128 v[160:163], v155 offset:2048
	ds_read_b128 v[164:167], v155 offset:3072
	v_add_u32_e32 v155, s52, v149
	ds_read_b128 v[168:171], v155
	ds_read_b128 v[172:175], v155 offset:1024
	ds_read_b128 v[176:179], v155 offset:2048
	ds_read_b128 v[180:183], v155 offset:3072
	s_add_u32 s30, s30, 0x100000
	s_addc_u32 s31, s31, 0
	s_mov_b32 m0, s36
	v_lshl_add_u64 v[234:235], s[30:31], 0, v[128:129]
	ds_read_b128 v[184:187], v153 offset:32768
	ds_read_b128 v[188:191], v153 offset:33792
	ds_read_b128 v[198:201], v153 offset:34816
	ds_read_b128 v[202:205], v153 offset:35840
	ds_read_b128 v[216:219], v153 offset:36864
	ds_read_b128 v[220:223], v153 offset:37888
	ds_read_b128 v[224:227], v153 offset:38912
	ds_read_b128 v[228:231], v153 offset:39936
	global_load_lds_dwordx4 v[234:235], off
	v_lshl_add_u64 v[234:235], s[30:31], 0, v[132:133]
	s_mov_b32 m0, s37
	s_nop 0
	global_load_lds_dwordx4 v[234:235], off
	s_waitcnt vmcnt(8) lgkmcnt(0)
	s_setprio 1
	s_barrier
	v_mfma_f32_16x16x32_bf16 v[124:127], v[144:147], v[184:187], v[124:127]
	v_mfma_f32_16x16x32_bf16 v[120:123], v[160:163], v[184:187], v[120:123]
	v_mfma_f32_16x16x32_bf16 v[108:111], v[144:147], v[198:201], v[108:111]
	v_mfma_f32_16x16x32_bf16 v[104:107], v[160:163], v[198:201], v[104:107]
	v_mfma_f32_16x16x32_bf16 v[92:95], v[144:147], v[216:219], v[92:95]
	v_mfma_f32_16x16x32_bf16 v[88:91], v[160:163], v[216:219], v[88:91]
	v_mfma_f32_16x16x32_bf16 v[76:79], v[144:147], v[224:227], v[76:79]
	v_mfma_f32_16x16x32_bf16 v[72:75], v[160:163], v[224:227], v[72:75]
	v_mfma_f32_16x16x32_bf16 v[124:127], v[156:159], v[188:191], v[124:127]
	v_mfma_f32_16x16x32_bf16 v[120:123], v[164:167], v[188:191], v[120:123]
	v_mfma_f32_16x16x32_bf16 v[108:111], v[156:159], v[202:205], v[108:111]
	v_mfma_f32_16x16x32_bf16 v[104:107], v[164:167], v[202:205], v[104:107]
	v_mfma_f32_16x16x32_bf16 v[92:95], v[156:159], v[220:223], v[92:95]
	v_mfma_f32_16x16x32_bf16 v[88:91], v[164:167], v[220:223], v[88:91]
	v_mfma_f32_16x16x32_bf16 v[76:79], v[156:159], v[228:231], v[76:79]
	v_mfma_f32_16x16x32_bf16 v[72:75], v[164:167], v[228:231], v[72:75]
	v_mfma_f32_16x16x32_bf16 v[116:119], v[168:171], v[184:187], v[116:119]
	v_mfma_f32_16x16x32_bf16 v[112:115], v[176:179], v[184:187], v[112:115]
	v_mfma_f32_16x16x32_bf16 v[100:103], v[168:171], v[198:201], v[100:103]
	v_mfma_f32_16x16x32_bf16 v[96:99], v[176:179], v[198:201], v[96:99]
	v_mfma_f32_16x16x32_bf16 v[84:87], v[168:171], v[216:219], v[84:87]
	v_mfma_f32_16x16x32_bf16 v[80:83], v[176:179], v[216:219], v[80:83]
	v_mfma_f32_16x16x32_bf16 v[68:71], v[168:171], v[224:227], v[68:71]
	v_mfma_f32_16x16x32_bf16 v[64:67], v[176:179], v[224:227], v[64:67]
	v_mfma_f32_16x16x32_bf16 v[116:119], v[172:175], v[188:191], v[116:119]
	v_mfma_f32_16x16x32_bf16 v[112:115], v[180:183], v[188:191], v[112:115]
	v_mfma_f32_16x16x32_bf16 v[100:103], v[172:175], v[202:205], v[100:103]
	v_mfma_f32_16x16x32_bf16 v[96:99], v[180:183], v[202:205], v[96:99]
	v_mfma_f32_16x16x32_bf16 v[84:87], v[172:175], v[220:223], v[84:87]
	v_mfma_f32_16x16x32_bf16 v[80:83], v[180:183], v[220:223], v[80:83]
	v_mfma_f32_16x16x32_bf16 v[68:71], v[172:175], v[228:231], v[68:71]
	v_mfma_f32_16x16x32_bf16 v[64:67], v[180:183], v[228:231], v[64:67]
	s_barrier
; #define PG8_STAGE(bufoff, gbase, voff) do { _Pragma("unroll") for (int _i = 0; _i < 2; ++_i) \
;         __builtin_amdgcn_global_load_lds((const unsigned*)((const char*)(gbase) + (voff)[_i]), (LAS unsigned*)(lds + (bufoff) + ldsw + _i * 8192), 16, 0, 0); } while (0)
; #define PG8_LDA(dst, b, h) do { _Pragma("unroll") for (int m = 0; m < 4; ++m) _Pragma("unroll") for (int k = 0; k < 2; ++k) dst[m][k] = *(const LAS bf16x8*)(lds + PG8_SA(b, h) + aoff + m * 2048 + k * 1024); } while (0)
; #define PG8_MMA(ai, bj, At, Bt) do { __builtin_amdgcn_s_setprio(1); _Pragma("unroll") for (int m = 0; m < 4; ++m) _Pragma("unroll") for (int n = 0; n < 2; ++n) _Pragma("unroll") for (int k = 0; k < 2; ++k) \
;         acc[ai][bj][m][n] = __builtin_amdgcn_mfma_f32_16x16x32_bf16(Bt[n][k], At[m][k], acc[ai][bj][m][n], 0, 0, 0); __builtin_amdgcn_s_setprio(0); } while (0)
; #define PG8_WAIT_V(n) asm volatile("s_waitcnt vmcnt(" #n ")" ::: "memory")
; #define PG8_WAIT_L(n) asm volatile("s_waitcnt lgkmcnt(" #n ")" ::: "memory")
; #define PG8_BAR __builtin_amdgcn_s_barrier()
; #define PG8_SCHED __builtin_amdgcn_sched_barrier(0)
; template <class Epi, bool ALIGN_EPI, bool SP2 = PG8_SP2_DEFAULT>
; __device__ __forceinline__ void gemm_phase(LAS unsigned char* lds, const Gemm g, const StaticOrder& S, const Epi& E) {
;     ...
;             PG8_LDA(At, 1, 1); PG8_STAGE(PG8_SB(1, 0), b3, voffB); PG8_STAGE(PG8_SB(1, 1), b3 + hstepB, voffB); PG8_STAGE(PG8_SA(1, 0), a3, voffA);
;             PG8_WAIT_V(8); PG8_WAIT_L(0); PG8_BAR; PG8_MMA(1, 0, At, B0); PG8_MMA(1, 1, At, B1); PG8_BAR; PG8_SCHED;
;     ...
;         if constexpr (ALIGN_EPI) { if (wr == 0) PG8_BAR; }
	s_setprio 0
	s_add_i32 s30, s51, s33
	v_lshl_add_u64 v[192:193], v[192:193], 0, s[14:15]
	s_mov_b32 m0, s30
	ds_read_b128 v[184:187], v153 offset:49152
	ds_read_b128 v[188:191], v153 offset:50176
	ds_read_b128 v[198:201], v153 offset:51200
	ds_read_b128 v[202:205], v153 offset:52224
	ds_read_b128 v[216:219], v153 offset:53248
	ds_read_b128 v[220:223], v153 offset:54272
	ds_read_b128 v[224:227], v153 offset:55296
	ds_read_b128 v[228:231], v153 offset:56320
	global_load_lds_dwordx4 v[192:193], off
	s_add_i32 m0, s30, 0x2000
	s_add_u32 s28, s28, 0x100080
	v_lshl_add_u64 v[192:193], v[206:207], 0, s[14:15]
	s_addc_u32 s29, s29, 0
	s_add_i32 s30, s52, s33
	global_load_lds_dwordx4 v[192:193], off
	v_lshl_add_u64 v[192:193], s[28:29], 0, v[130:131]
	s_mov_b32 m0, s30
	s_nop 0
	global_load_lds_dwordx4 v[192:193], off
	v_lshl_add_u64 v[192:193], s[28:29], 0, v[134:135]
	s_add_i32 m0, s30, 0x2000
	s_nop 0
	global_load_lds_dwordx4 v[192:193], off
	v_lshl_add_u64 v[192:193], v[210:211], 0, s[14:15]
	s_mov_b32 m0, s39
	s_nop 0
	global_load_lds_dwordx4 v[192:193], off
	v_lshl_add_u64 v[192:193], v[232:233], 0, s[14:15]
	s_mov_b32 m0, s40
	s_nop 0
	global_load_lds_dwordx4 v[192:193], off
	s_waitcnt vmcnt(8) lgkmcnt(0)
	s_setprio 1
	s_barrier
	v_mfma_f32_16x16x32_bf16 v[60:63], v[144:147], v[184:187], v[60:63]
	v_mfma_f32_16x16x32_bf16 v[56:59], v[160:163], v[184:187], v[56:59]
	v_mfma_f32_16x16x32_bf16 v[44:47], v[144:147], v[198:201], v[44:47]
	v_mfma_f32_16x16x32_bf16 v[40:43], v[160:163], v[198:201], v[40:43]
	v_mfma_f32_16x16x32_bf16 v[28:31], v[144:147], v[216:219], v[28:31]
	v_mfma_f32_16x16x32_bf16 v[24:27], v[160:163], v[216:219], v[24:27]
	v_mfma_f32_16x16x32_bf16 v[12:15], v[144:147], v[224:227], v[12:15]
	v_mfma_f32_16x16x32_bf16 v[8:11], v[160:163], v[224:227], v[8:11]
	v_mfma_f32_16x16x32_bf16 v[60:63], v[156:159], v[188:191], v[60:63]
	v_mfma_f32_16x16x32_bf16 v[56:59], v[164:167], v[188:191], v[56:59]
	v_mfma_f32_16x16x32_bf16 v[44:47], v[156:159], v[202:205], v[44:47]
	v_mfma_f32_16x16x32_bf16 v[40:43], v[164:167], v[202:205], v[40:43]
	v_mfma_f32_16x16x32_bf16 v[28:31], v[156:159], v[220:223], v[28:31]
	v_mfma_f32_16x16x32_bf16 v[24:27], v[164:167], v[220:223], v[24:27]
	v_mfma_f32_16x16x32_bf16 v[12:15], v[156:159], v[228:231], v[12:15]
	v_mfma_f32_16x16x32_bf16 v[8:11], v[164:167], v[228:231], v[8:11]
	v_mfma_f32_16x16x32_bf16 v[52:55], v[168:171], v[184:187], v[52:55]
	v_mfma_f32_16x16x32_bf16 v[48:51], v[176:179], v[184:187], v[48:51]
	v_mfma_f32_16x16x32_bf16 v[36:39], v[168:171], v[198:201], v[36:39]
	v_mfma_f32_16x16x32_bf16 v[32:35], v[176:179], v[198:201], v[32:35]
	v_mfma_f32_16x16x32_bf16 v[20:23], v[168:171], v[216:219], v[20:23]
	v_mfma_f32_16x16x32_bf16 v[16:19], v[176:179], v[216:219], v[16:19]
	v_mfma_f32_16x16x32_bf16 v[4:7], v[168:171], v[224:227], v[4:7]
	v_mfma_f32_16x16x32_bf16 v[0:3], v[176:179], v[224:227], v[0:3]
	v_mfma_f32_16x16x32_bf16 v[52:55], v[172:175], v[188:191], v[52:55]
	v_mfma_f32_16x16x32_bf16 v[48:51], v[180:183], v[188:191], v[48:51]
	v_mfma_f32_16x16x32_bf16 v[36:39], v[172:175], v[202:205], v[36:39]
	v_mfma_f32_16x16x32_bf16 v[32:35], v[180:183], v[202:205], v[32:35]
	v_mfma_f32_16x16x32_bf16 v[20:23], v[172:175], v[220:223], v[20:23]
	v_mfma_f32_16x16x32_bf16 v[16:19], v[180:183], v[220:223], v[16:19]
	v_mfma_f32_16x16x32_bf16 v[4:7], v[172:175], v[228:231], v[4:7]
	v_mfma_f32_16x16x32_bf16 v[0:3], v[180:183], v[228:231], v[0:3]
	s_barrier
	s_setprio 0
	s_add_i32 s50, s50, 2
	s_add_u32 s26, s26, 0x100
	s_addc_u32 s27, s27, 0
	s_add_u32 s48, s48, 0x100
	s_addc_u32 s49, s49, 0
	s_cmp_gt_u32 s50, 61
	s_cbranch_scc0 .LBB0_506
	s_and_b64 vcc, exec, s[16:17]
	s_cbranch_vccz .LBB0_509
	s_barrier

; #define PG8_STAGE(bufoff, gbase, voff) do { _Pragma("unroll") for (int _i = 0; _i < 2; ++_i) \
;         __builtin_amdgcn_global_load_lds((const unsigned*)((const char*)(gbase) + (voff)[_i]), (LAS unsigned*)(lds + (bufoff) + ldsw + _i * 8192), 16, 0, 0); } while (0)
; #define PG8_LDA(dst, b, h) do { _Pragma("unroll") for (int m = 0; m < 4; ++m) _Pragma("unroll") for (int k = 0; k < 2; ++k) dst[m][k] = *(const LAS bf16x8*)(lds + PG8_SA(b, h) + aoff + m * 2048 + k * 1024); } while (0)
; #define PG8_LDB(dst, b, h) do { _Pragma("unroll") for (int n = 0; n < 2; ++n) _Pragma("unroll") for (int k = 0; k < 2; ++k) dst[n][k] = *(const LAS bf16x8*)(lds + PG8_SB(b, h) + boff + n * 2048 + k * 1024); } while (0)
; #define PG8_MMA(ai, bj, At, Bt) do { __builtin_amdgcn_s_setprio(1); _Pragma("unroll") for (int m = 0; m < 4; ++m) _Pragma("unroll") for (int n = 0; n < 2; ++n) _Pragma("unroll") for (int k = 0; k < 2; ++k) \
;         acc[ai][bj][m][n] = __builtin_amdgcn_mfma_f32_16x16x32_bf16(Bt[n][k], At[m][k], acc[ai][bj][m][n], 0, 0, 0); __builtin_amdgcn_s_setprio(0); } while (0)
; #define PG8_WAIT_V(n) asm volatile("s_waitcnt vmcnt(" #n ")" ::: "memory")
; template <class Epi, bool ALIGN_EPI, bool SP2 = PG8_SP2_DEFAULT>
; __device__ __forceinline__ void gemm_phase(LAS unsigned char* lds, const Gemm g, const StaticOrder& S, const Epi& E) {
;     ...
;         const char* nA = has_next ? PG8_ABASE(nxt) : cA; const char* nB = has_next ? (const char*)g.Bt + (size_t)nxt.pn * tstepB : cB;
;         for (int t = 0; t < nt; t += 2) {
;             const bool last = (t == nt - 2);
;             const char* a1 = cA + (size_t)(t + 1) * kstep;
;             const char* a2 = last ? nA : cA + (size_t)(t + 2) * kstep; const char* b2 = last ? nB : cB + (size_t)(t + 2) * kstep;
;             const char* a3 = a2 + kstep; const char* b3 = b2 + kstep;
;             if constexpr (SP2) {
;             PG8_LDB(B0, 0, 0); PG8_LDB(B1, 0, 1); PG8_SCHED; PG8_LDA(At, 0, 0); PG8_STAGE(PG8_SA(1, 1), a1 + hstepA, voffA);
;             PG8_WAIT_V(8); PG8_WAIT_L(0); PG8_BAR; PG8_MMA(0, 0, At, B0); PG8_MMA(0, 1, At, B1); PG8_BAR; PG8_SCHED;
;             PG8_LDA(At, 0, 1); PG8_STAGE(PG8_SB(0, 0), b2, voffB); PG8_STAGE(PG8_SB(0, 1), b2 + hstepB, voffB); PG8_STAGE(PG8_SA(0, 0), a2, voffA);
;             PG8_WAIT_V(8); PG8_WAIT_L(0); PG8_BAR; PG8_MMA(1, 0, At, B0); PG8_MMA(1, 1, At, B1); PG8_BAR; PG8_SCHED;
.LBB0_598:
	ds_read_b128 v[146:149], v155
	ds_read_b128 v[160:163], v155 offset:1024
	ds_read_b128 v[164:167], v155 offset:2048
	ds_read_b128 v[168:171], v155 offset:3072
	ds_read_b128 v[172:175], v156
	ds_read_b128 v[176:179], v156 offset:1024
	ds_read_b128 v[180:183], v156 offset:2048
	ds_read_b128 v[184:187], v156 offset:3072
	s_add_u32 s24, s22, 0xfff00080
	s_addc_u32 s25, s23, -1
	s_cmp_eq_u32 s47, 60
	s_cselect_b32 s27, s3, s25
	s_cselect_b32 s26, s7, s24
	s_cselect_b32 s25, s9, s45
	s_cselect_b32 s24, s17, s44
	v_lshl_add_u64 v[192:193], s[22:23], 0, v[138:139]
	s_add_i32 m0, s30, 0xc000
	ds_read_b128 v[188:191], v157
	ds_read_b128 v[198:201], v157 offset:1024
	ds_read_b128 v[202:205], v157 offset:2048
	ds_read_b128 v[214:217], v157 offset:3072
	ds_read_b128 v[218:221], v157 offset:4096
	ds_read_b128 v[222:225], v157 offset:5120
	ds_read_b128 v[226:229], v157 offset:6144
	ds_read_b128 v[230:233], v157 offset:7168
	global_load_lds_dwordx4 v[192:193], off
	v_lshl_add_u64 v[192:193], s[22:23], 0, v[140:141]
	s_add_i32 m0, s30, 0xe000
	s_nop 0
	global_load_lds_dwordx4 v[192:193], off
	s_waitcnt vmcnt(8) lgkmcnt(0)
	s_setprio 1
	s_barrier
	v_mfma_f32_16x16x32_bf16 v[124:127], v[146:149], v[188:191], v[124:127]
	v_mfma_f32_16x16x32_bf16 v[120:123], v[164:167], v[188:191], v[120:123]
	v_mfma_f32_16x16x32_bf16 v[108:111], v[146:149], v[202:205], v[108:111]
	v_mfma_f32_16x16x32_bf16 v[104:107], v[164:167], v[202:205], v[104:107]
	v_mfma_f32_16x16x32_bf16 v[92:95], v[146:149], v[218:221], v[92:95]
	v_mfma_f32_16x16x32_bf16 v[88:91], v[164:167], v[218:221], v[88:91]
	v_mfma_f32_16x16x32_bf16 v[76:79], v[146:149], v[226:229], v[76:79]
	v_mfma_f32_16x16x32_bf16 v[72:75], v[164:167], v[226:229], v[72:75]
	v_mfma_f32_16x16x32_bf16 v[124:127], v[160:163], v[198:201], v[124:127]
	v_mfma_f32_16x16x32_bf16 v[120:123], v[168:171], v[198:201], v[120:123]
	v_mfma_f32_16x16x32_bf16 v[108:111], v[160:163], v[214:217], v[108:111]
	v_mfma_f32_16x16x32_bf16 v[104:107], v[168:171], v[214:217], v[104:107]
	v_mfma_f32_16x16x32_bf16 v[92:95], v[160:163], v[222:225], v[92:95]
	v_mfma_f32_16x16x32_bf16 v[88:91], v[168:171], v[222:225], v[88:91]
	v_mfma_f32_16x16x32_bf16 v[76:79], v[160:163], v[230:233], v[76:79]
	v_mfma_f32_16x16x32_bf16 v[72:75], v[168:171], v[230:233], v[72:75]
	v_mfma_f32_16x16x32_bf16 v[116:119], v[172:175], v[188:191], v[116:119]
	v_mfma_f32_16x16x32_bf16 v[112:115], v[180:183], v[188:191], v[112:115]
	v_mfma_f32_16x16x32_bf16 v[100:103], v[172:175], v[202:205], v[100:103]
	v_mfma_f32_16x16x32_bf16 v[96:99], v[180:183], v[202:205], v[96:99]
	v_mfma_f32_16x16x32_bf16 v[84:87], v[172:175], v[218:221], v[84:87]
	v_mfma_f32_16x16x32_bf16 v[80:83], v[180:183], v[218:221], v[80:83]
	v_mfma_f32_16x16x32_bf16 v[68:71], v[172:175], v[226:229], v[68:71]
	v_mfma_f32_16x16x32_bf16 v[64:67], v[180:183], v[226:229], v[64:67]
	v_mfma_f32_16x16x32_bf16 v[116:119], v[176:179], v[198:201], v[116:119]
	v_mfma_f32_16x16x32_bf16 v[112:115], v[184:187], v[198:201], v[112:115]
	v_mfma_f32_16x16x32_bf16 v[100:103], v[176:179], v[214:217], v[100:103]
	v_mfma_f32_16x16x32_bf16 v[96:99], v[184:187], v[214:217], v[96:99]
	v_mfma_f32_16x16x32_bf16 v[84:87], v[176:179], v[222:225], v[84:87]
	v_mfma_f32_16x16x32_bf16 v[80:83], v[184:187], v[222:225], v[80:83]
	v_mfma_f32_16x16x32_bf16 v[68:71], v[176:179], v[230:233], v[68:71]
	v_mfma_f32_16x16x32_bf16 v[64:67], v[184:187], v[230:233], v[64:67]
	s_barrier
	s_setprio 0
	s_add_i32 s48, s41, s29
	v_lshl_add_u64 v[192:193], s[24:25], 0, v[130:131]
	s_mov_b32 m0, s48
	ds_read_b128 v[188:191], v157 offset:16384
	ds_read_b128 v[198:201], v157 offset:17408
	ds_read_b128 v[202:205], v157 offset:18432
	ds_read_b128 v[214:217], v157 offset:19456
	ds_read_b128 v[218:221], v157 offset:20480
	ds_read_b128 v[222:225], v157 offset:21504
	ds_read_b128 v[226:229], v157 offset:22528
	ds_read_b128 v[230:233], v157 offset:23552
	global_load_lds_dwordx4 v[192:193], off
	s_add_i32 m0, s48, 0x2000
	s_add_u32 s48, s24, 0x100000
	v_lshl_add_u64 v[206:207], s[24:25], 0, v[134:135]
	s_addc_u32 s49, s25, 0
	s_add_i32 s50, s42, s29
	global_load_lds_dwordx4 v[206:207], off
	v_lshl_add_u64 v[210:211], s[48:49], 0, v[130:131]
	s_mov_b32 m0, s50
	v_lshl_add_u64 v[234:235], s[26:27], 0, v[132:133]
	global_load_lds_dwordx4 v[210:211], off
	v_lshl_add_u64 v[210:211], s[48:49], 0, v[134:135]
	s_add_i32 m0, s50, 0x2000
	s_nop 0
	global_load_lds_dwordx4 v[210:211], off
	v_lshl_add_u64 v[210:211], s[26:27], 0, v[128:129]
	s_mov_b32 m0, s30
	s_nop 0
	global_load_lds_dwordx4 v[210:211], off
	s_mov_b32 m0, s31
	s_nop 0
	global_load_lds_dwordx4 v[234:235], off
	s_waitcnt vmcnt(8) lgkmcnt(0)
	s_setprio 1
	s_barrier
; #define PG8_STAGE(bufoff, gbase, voff) do { _Pragma("unroll") for (int _i = 0; _i < 2; ++_i) \
;         __builtin_amdgcn_global_load_lds((const unsigned*)((const char*)(gbase) + (voff)[_i]), (LAS unsigned*)(lds + (bufoff) + ldsw + _i * 8192), 16, 0, 0); } while (0)
; #define PG8_LDA(dst, b, h) do { _Pragma("unroll") for (int m = 0; m < 4; ++m) _Pragma("unroll") for (int k = 0; k < 2; ++k) dst[m][k] = *(const LAS bf16x8*)(lds + PG8_SA(b, h) + aoff + m * 2048 + k * 1024); } while (0)
; #define PG8_LDB(dst, b, h) do { _Pragma("unroll") for (int n = 0; n < 2; ++n) _Pragma("unroll") for (int k = 0; k < 2; ++k) dst[n][k] = *(const LAS bf16x8*)(lds + PG8_SB(b, h) + boff + n * 2048 + k * 1024); } while (0)
; #define PG8_MMA(ai, bj, At, Bt) do { __builtin_amdgcn_s_setprio(1); _Pragma("unroll") for (int m = 0; m < 4; ++m) _Pragma("unroll") for (int n = 0; n < 2; ++n) _Pragma("unroll") for (int k = 0; k < 2; ++k) \
;         acc[ai][bj][m][n] = __builtin_amdgcn_mfma_f32_16x16x32_bf16(Bt[n][k], At[m][k], acc[ai][bj][m][n], 0, 0, 0); __builtin_amdgcn_s_setprio(0); } while (0)
; #define PG8_WAIT_V(n) asm volatile("s_waitcnt vmcnt(" #n ")" ::: "memory")
; #define PG8_WAIT_L(n) asm volatile("s_waitcnt lgkmcnt(" #n ")" ::: "memory")
; #define PG8_BAR __builtin_amdgcn_s_barrier()
; #define PG8_SCHED __builtin_amdgcn_sched_barrier(0)
; template <class Epi, bool ALIGN_EPI, bool SP2 = PG8_SP2_DEFAULT>
; __device__ __forceinline__ void gemm_phase(LAS unsigned char* lds, const Gemm g, const StaticOrder& S, const Epi& E) {
;     ...
;             PG8_WAIT_V(8); PG8_WAIT_L(0); PG8_BAR; PG8_MMA(1, 0, At, B0); PG8_MMA(1, 1, At, B1); PG8_BAR; PG8_SCHED;
;             PG8_LDB(B0, 1, 0); PG8_LDB(B1, 1, 1); PG8_SCHED; PG8_LDA(At, 1, 0); PG8_STAGE(PG8_SA(0, 1), a2 + hstepA, voffA);
;             PG8_WAIT_V(8); PG8_WAIT_L(0); PG8_BAR; PG8_MMA(0, 0, At, B0); PG8_MMA(0, 1, At, B1); PG8_BAR; PG8_SCHED;
	v_mfma_f32_16x16x32_bf16 v[60:63], v[146:149], v[188:191], v[60:63]
	v_mfma_f32_16x16x32_bf16 v[56:59], v[164:167], v[188:191], v[56:59]
	v_mfma_f32_16x16x32_bf16 v[44:47], v[146:149], v[202:205], v[44:47]
	v_mfma_f32_16x16x32_bf16 v[40:43], v[164:167], v[202:205], v[40:43]
	v_mfma_f32_16x16x32_bf16 v[28:31], v[146:149], v[218:221], v[28:31]
	v_mfma_f32_16x16x32_bf16 v[24:27], v[164:167], v[218:221], v[24:27]
	v_mfma_f32_16x16x32_bf16 v[12:15], v[146:149], v[226:229], v[12:15]
	v_mfma_f32_16x16x32_bf16 v[8:11], v[164:167], v[226:229], v[8:11]
	v_mfma_f32_16x16x32_bf16 v[60:63], v[160:163], v[198:201], v[60:63]
	v_mfma_f32_16x16x32_bf16 v[56:59], v[168:171], v[198:201], v[56:59]
	v_mfma_f32_16x16x32_bf16 v[44:47], v[160:163], v[214:217], v[44:47]
	v_mfma_f32_16x16x32_bf16 v[40:43], v[168:171], v[214:217], v[40:43]
	v_mfma_f32_16x16x32_bf16 v[28:31], v[160:163], v[222:225], v[28:31]
	v_mfma_f32_16x16x32_bf16 v[24:27], v[168:171], v[222:225], v[24:27]
	v_mfma_f32_16x16x32_bf16 v[12:15], v[160:163], v[230:233], v[12:15]
	v_mfma_f32_16x16x32_bf16 v[8:11], v[168:171], v[230:233], v[8:11]
	v_mfma_f32_16x16x32_bf16 v[52:55], v[172:175], v[188:191], v[52:55]
	v_mfma_f32_16x16x32_bf16 v[48:51], v[180:183], v[188:191], v[48:51]
	v_mfma_f32_16x16x32_bf16 v[36:39], v[172:175], v[202:205], v[36:39]
	v_mfma_f32_16x16x32_bf16 v[32:35], v[180:183], v[202:205], v[32:35]
	v_mfma_f32_16x16x32_bf16 v[20:23], v[172:175], v[218:221], v[20:23]
	v_mfma_f32_16x16x32_bf16 v[16:19], v[180:183], v[218:221], v[16:19]
	v_mfma_f32_16x16x32_bf16 v[4:7], v[172:175], v[226:229], v[4:7]
	v_mfma_f32_16x16x32_bf16 v[0:3], v[180:183], v[226:229], v[0:3]
	v_mfma_f32_16x16x32_bf16 v[52:55], v[176:179], v[198:201], v[52:55]
	v_mfma_f32_16x16x32_bf16 v[48:51], v[184:187], v[198:201], v[48:51]
	v_mfma_f32_16x16x32_bf16 v[36:39], v[176:179], v[214:217], v[36:39]
	v_mfma_f32_16x16x32_bf16 v[32:35], v[184:187], v[214:217], v[32:35]
	v_mfma_f32_16x16x32_bf16 v[20:23], v[176:179], v[222:225], v[20:23]
	v_mfma_f32_16x16x32_bf16 v[16:19], v[184:187], v[222:225], v[16:19]
	v_mfma_f32_16x16x32_bf16 v[4:7], v[176:179], v[230:233], v[4:7]
	v_mfma_f32_16x16x32_bf16 v[0:3], v[184:187], v[230:233], v[0:3]
	s_barrier
	s_setprio 0
	s_add_i32 s48, 0, 0x18000
	v_add_u32_e32 v150, s48, v152
	s_add_i32 s49, 0, 0x1c000
	ds_read_b128 v[146:149], v150
	ds_read_b128 v[160:163], v150 offset:1024
	ds_read_b128 v[164:167], v150 offset:2048
	ds_read_b128 v[168:171], v150 offset:3072
	v_add_u32_e32 v150, s49, v152
	ds_read_b128 v[172:175], v150
	ds_read_b128 v[176:179], v150 offset:1024
	ds_read_b128 v[180:183], v150 offset:2048
	ds_read_b128 v[184:187], v150 offset:3072
	s_add_u32 s26, s26, 0x100000
	s_addc_u32 s27, s27, 0
	s_mov_b32 m0, s33
	v_lshl_add_u64 v[236:237], s[26:27], 0, v[128:129]
	ds_read_b128 v[188:191], v157 offset:32768
	ds_read_b128 v[198:201], v157 offset:33792
	ds_read_b128 v[202:205], v157 offset:34816
	ds_read_b128 v[214:217], v157 offset:35840
	ds_read_b128 v[218:221], v157 offset:36864
	ds_read_b128 v[222:225], v157 offset:37888
	ds_read_b128 v[226:229], v157 offset:38912
	ds_read_b128 v[230:233], v157 offset:39936
	global_load_lds_dwordx4 v[236:237], off
	v_lshl_add_u64 v[236:237], s[26:27], 0, v[132:133]
	s_mov_b32 m0, s34
	s_nop 0
	global_load_lds_dwordx4 v[236:237], off
	s_waitcnt vmcnt(8) lgkmcnt(0)
	s_setprio 1
	s_barrier
	v_mfma_f32_16x16x32_bf16 v[124:127], v[146:149], v[188:191], v[124:127]
	v_mfma_f32_16x16x32_bf16 v[120:123], v[164:167], v[188:191], v[120:123]
	v_mfma_f32_16x16x32_bf16 v[108:111], v[146:149], v[202:205], v[108:111]
	v_mfma_f32_16x16x32_bf16 v[104:107], v[164:167], v[202:205], v[104:107]
	v_mfma_f32_16x16x32_bf16 v[92:95], v[146:149], v[218:221], v[92:95]
	v_mfma_f32_16x16x32_bf16 v[88:91], v[164:167], v[218:221], v[88:91]
	v_mfma_f32_16x16x32_bf16 v[76:79], v[146:149], v[226:229], v[76:79]
	v_mfma_f32_16x16x32_bf16 v[72:75], v[164:167], v[226:229], v[72:75]
	v_mfma_f32_16x16x32_bf16 v[124:127], v[160:163], v[198:201], v[124:127]
	v_mfma_f32_16x16x32_bf16 v[120:123], v[168:171], v[198:201], v[120:123]
	v_mfma_f32_16x16x32_bf16 v[108:111], v[160:163], v[214:217], v[108:111]
	v_mfma_f32_16x16x32_bf16 v[104:107], v[168:171], v[214:217], v[104:107]
	v_mfma_f32_16x16x32_bf16 v[92:95], v[160:163], v[222:225], v[92:95]
	v_mfma_f32_16x16x32_bf16 v[88:91], v[168:171], v[222:225], v[88:91]
	v_mfma_f32_16x16x32_bf16 v[76:79], v[160:163], v[230:233], v[76:79]
	v_mfma_f32_16x16x32_bf16 v[72:75], v[168:171], v[230:233], v[72:75]
	v_mfma_f32_16x16x32_bf16 v[116:119], v[172:175], v[188:191], v[116:119]
	v_mfma_f32_16x16x32_bf16 v[112:115], v[180:183], v[188:191], v[112:115]
	v_mfma_f32_16x16x32_bf16 v[100:103], v[172:175], v[202:205], v[100:103]
	v_mfma_f32_16x16x32_bf16 v[96:99], v[180:183], v[202:205], v[96:99]
	v_mfma_f32_16x16x32_bf16 v[84:87], v[172:175], v[218:221], v[84:87]
	v_mfma_f32_16x16x32_bf16 v[80:83], v[180:183], v[218:221], v[80:83]
	v_mfma_f32_16x16x32_bf16 v[68:71], v[172:175], v[226:229], v[68:71]
	v_mfma_f32_16x16x32_bf16 v[64:67], v[180:183], v[226:229], v[64:67]
	v_mfma_f32_16x16x32_bf16 v[116:119], v[176:179], v[198:201], v[116:119]
	v_mfma_f32_16x16x32_bf16 v[112:115], v[184:187], v[198:201], v[112:115]
	v_mfma_f32_16x16x32_bf16 v[100:103], v[176:179], v[214:217], v[100:103]
	v_mfma_f32_16x16x32_bf16 v[96:99], v[184:187], v[214:217], v[96:99]
	v_mfma_f32_16x16x32_bf16 v[84:87], v[176:179], v[222:225], v[84:87]
	v_mfma_f32_16x16x32_bf16 v[80:83], v[184:187], v[222:225], v[80:83]
	v_mfma_f32_16x16x32_bf16 v[68:71], v[176:179], v[230:233], v[68:71]
	v_mfma_f32_16x16x32_bf16 v[64:67], v[184:187], v[230:233], v[64:67]
	s_barrier
; #define PG8_STAGE(bufoff, gbase, voff) do { _Pragma("unroll") for (int _i = 0; _i < 2; ++_i) \
;         __builtin_amdgcn_global_load_lds((const unsigned*)((const char*)(gbase) + (voff)[_i]), (LAS unsigned*)(lds + (bufoff) + ldsw + _i * 8192), 16, 0, 0); } while (0)
; #define PG8_LDA(dst, b, h) do { _Pragma("unroll") for (int m = 0; m < 4; ++m) _Pragma("unroll") for (int k = 0; k < 2; ++k) dst[m][k] = *(const LAS bf16x8*)(lds + PG8_SA(b, h) + aoff + m * 2048 + k * 1024); } while (0)
; #define PG8_MMA(ai, bj, At, Bt) do { __builtin_amdgcn_s_setprio(1); _Pragma("unroll") for (int m = 0; m < 4; ++m) _Pragma("unroll") for (int n = 0; n < 2; ++n) _Pragma("unroll") for (int k = 0; k < 2; ++k) \
;         acc[ai][bj][m][n] = __builtin_amdgcn_mfma_f32_16x16x32_bf16(Bt[n][k], At[m][k], acc[ai][bj][m][n], 0, 0, 0); __builtin_amdgcn_s_setprio(0); } while (0)
; #define PG8_WAIT_V(n) asm volatile("s_waitcnt vmcnt(" #n ")" ::: "memory")
; #define PG8_WAIT_L(n) asm volatile("s_waitcnt lgkmcnt(" #n ")" ::: "memory")
; #define PG8_BAR __builtin_amdgcn_s_barrier()
; #define PG8_SCHED __builtin_amdgcn_sched_barrier(0)
; template <class Epi, bool ALIGN_EPI, bool SP2 = PG8_SP2_DEFAULT>
; __device__ __forceinline__ void gemm_phase(LAS unsigned char* lds, const Gemm g, const StaticOrder& S, const Epi& E) {
;     ...
;             PG8_LDA(At, 1, 1); PG8_STAGE(PG8_SB(1, 0), b3, voffB); PG8_STAGE(PG8_SB(1, 1), b3 + hstepB, voffB); PG8_STAGE(PG8_SA(1, 0), a3, voffA);
;             PG8_WAIT_V(8); PG8_WAIT_L(0); PG8_BAR; PG8_MMA(1, 0, At, B0); PG8_MMA(1, 1, At, B1); PG8_BAR; PG8_SCHED;
;     ...
;         if constexpr (ALIGN_EPI) { if (wr == 0) PG8_BAR; }
	s_setprio 0
	s_add_i32 s26, s48, s29
	v_lshl_add_u64 v[192:193], v[192:193], 0, s[12:13]
	s_mov_b32 m0, s26
	ds_read_b128 v[188:191], v157 offset:49152
	ds_read_b128 v[198:201], v157 offset:50176
	ds_read_b128 v[202:205], v157 offset:51200
	ds_read_b128 v[214:217], v157 offset:52224
	ds_read_b128 v[218:221], v157 offset:53248
	ds_read_b128 v[222:225], v157 offset:54272
	ds_read_b128 v[226:229], v157 offset:55296
	ds_read_b128 v[230:233], v157 offset:56320
	global_load_lds_dwordx4 v[192:193], off
	s_add_i32 m0, s26, 0x2000
	s_add_u32 s24, s24, 0x100080
	v_lshl_add_u64 v[192:193], v[206:207], 0, s[12:13]
	s_addc_u32 s25, s25, 0
	s_add_i32 s26, s49, s29
	global_load_lds_dwordx4 v[192:193], off
	v_lshl_add_u64 v[192:193], s[24:25], 0, v[130:131]
	s_mov_b32 m0, s26
	s_nop 0
	global_load_lds_dwordx4 v[192:193], off
	v_lshl_add_u64 v[192:193], s[24:25], 0, v[134:135]
	s_add_i32 m0, s26, 0x2000
	s_nop 0
	global_load_lds_dwordx4 v[192:193], off
	v_lshl_add_u64 v[192:193], v[210:211], 0, s[12:13]
	s_mov_b32 m0, s36
	s_nop 0
	global_load_lds_dwordx4 v[192:193], off
	v_lshl_add_u64 v[192:193], v[234:235], 0, s[12:13]
	s_mov_b32 m0, s37
	s_nop 0
	global_load_lds_dwordx4 v[192:193], off
	s_waitcnt vmcnt(8) lgkmcnt(0)
	s_setprio 1
	s_barrier
	v_mfma_f32_16x16x32_bf16 v[60:63], v[146:149], v[188:191], v[60:63]
	v_mfma_f32_16x16x32_bf16 v[56:59], v[164:167], v[188:191], v[56:59]
	v_mfma_f32_16x16x32_bf16 v[44:47], v[146:149], v[202:205], v[44:47]
	v_mfma_f32_16x16x32_bf16 v[40:43], v[164:167], v[202:205], v[40:43]
	v_mfma_f32_16x16x32_bf16 v[28:31], v[146:149], v[218:221], v[28:31]
	v_mfma_f32_16x16x32_bf16 v[24:27], v[164:167], v[218:221], v[24:27]
	v_mfma_f32_16x16x32_bf16 v[12:15], v[146:149], v[226:229], v[12:15]
	v_mfma_f32_16x16x32_bf16 v[8:11], v[164:167], v[226:229], v[8:11]
	v_mfma_f32_16x16x32_bf16 v[60:63], v[160:163], v[198:201], v[60:63]
	v_mfma_f32_16x16x32_bf16 v[56:59], v[168:171], v[198:201], v[56:59]
	v_mfma_f32_16x16x32_bf16 v[44:47], v[160:163], v[214:217], v[44:47]
	v_mfma_f32_16x16x32_bf16 v[40:43], v[168:171], v[214:217], v[40:43]
	v_mfma_f32_16x16x32_bf16 v[28:31], v[160:163], v[222:225], v[28:31]
	v_mfma_f32_16x16x32_bf16 v[24:27], v[168:171], v[222:225], v[24:27]
	v_mfma_f32_16x16x32_bf16 v[12:15], v[160:163], v[230:233], v[12:15]
	v_mfma_f32_16x16x32_bf16 v[8:11], v[168:171], v[230:233], v[8:11]
	v_mfma_f32_16x16x32_bf16 v[52:55], v[172:175], v[188:191], v[52:55]
	v_mfma_f32_16x16x32_bf16 v[48:51], v[180:183], v[188:191], v[48:51]
	v_mfma_f32_16x16x32_bf16 v[36:39], v[172:175], v[202:205], v[36:39]
	v_mfma_f32_16x16x32_bf16 v[32:35], v[180:183], v[202:205], v[32:35]
	v_mfma_f32_16x16x32_bf16 v[20:23], v[172:175], v[218:221], v[20:23]
	v_mfma_f32_16x16x32_bf16 v[16:19], v[180:183], v[218:221], v[16:19]
	v_mfma_f32_16x16x32_bf16 v[4:7], v[172:175], v[226:229], v[4:7]
	v_mfma_f32_16x16x32_bf16 v[0:3], v[180:183], v[226:229], v[0:3]
	v_mfma_f32_16x16x32_bf16 v[52:55], v[176:179], v[198:201], v[52:55]
	v_mfma_f32_16x16x32_bf16 v[48:51], v[184:187], v[198:201], v[48:51]
	v_mfma_f32_16x16x32_bf16 v[36:39], v[176:179], v[214:217], v[36:39]
	v_mfma_f32_16x16x32_bf16 v[32:35], v[184:187], v[214:217], v[32:35]
	v_mfma_f32_16x16x32_bf16 v[20:23], v[176:179], v[222:225], v[20:23]
	v_mfma_f32_16x16x32_bf16 v[16:19], v[184:187], v[222:225], v[16:19]
	v_mfma_f32_16x16x32_bf16 v[4:7], v[176:179], v[230:233], v[4:7]
	v_mfma_f32_16x16x32_bf16 v[0:3], v[184:187], v[230:233], v[0:3]
	s_barrier
	s_setprio 0
	s_add_i32 s47, s47, 2
	s_add_u32 s22, s22, 0x100
	s_addc_u32 s23, s23, 0
	s_add_u32 s44, s44, 0x100
	s_addc_u32 s45, s45, 0
	s_cmp_gt_u32 s47, 61
	s_cbranch_scc0 .LBB0_598
	s_and_b64 vcc, exec, s[14:15]
	s_cbranch_vccz .LBB0_601
	s_barrier

; #define PG8_STAGE(bufoff, gbase, voff) do { _Pragma("unroll") for (int _i = 0; _i < 2; ++_i) \
;         __builtin_amdgcn_global_load_lds((const unsigned*)((const char*)(gbase) + (voff)[_i]), (LAS unsigned*)(lds + (bufoff) + ldsw + _i * 8192), 16, 0, 0); } while (0)
; #define PG8_LDA(dst, b, h) do { _Pragma("unroll") for (int m = 0; m < 4; ++m) _Pragma("unroll") for (int k = 0; k < 2; ++k) dst[m][k] = *(const LAS bf16x8*)(lds + PG8_SA(b, h) + aoff + m * 2048 + k * 1024); } while (0)
; #define PG8_LDB(dst, b, h) do { _Pragma("unroll") for (int n = 0; n < 2; ++n) _Pragma("unroll") for (int k = 0; k < 2; ++k) dst[n][k] = *(const LAS bf16x8*)(lds + PG8_SB(b, h) + boff + n * 2048 + k * 1024); } while (0)
; #define PG8_MMA(ai, bj, At, Bt) do { __builtin_amdgcn_s_setprio(1); _Pragma("unroll") for (int m = 0; m < 4; ++m) _Pragma("unroll") for (int n = 0; n < 2; ++n) _Pragma("unroll") for (int k = 0; k < 2; ++k) \
;         acc[ai][bj][m][n] = __builtin_amdgcn_mfma_f32_16x16x32_bf16(Bt[n][k], At[m][k], acc[ai][bj][m][n], 0, 0, 0); __builtin_amdgcn_s_setprio(0); } while (0)
; #define PG8_WAIT_V(n) asm volatile("s_waitcnt vmcnt(" #n ")" ::: "memory")
; template <class Epi, bool ALIGN_EPI, bool SP2 = PG8_SP2_DEFAULT>
; __device__ __forceinline__ void gemm_phase(LAS unsigned char* lds, const Gemm g, const StaticOrder& S, const Epi& E) {
;     ...
;         const char* nA = has_next ? PG8_ABASE(nxt) : cA; const char* nB = has_next ? (const char*)g.Bt + (size_t)nxt.pn * tstepB : cB;
;         for (int t = 0; t < nt; t += 2) {
;             const bool last = (t == nt - 2);
;             const char* a1 = cA + (size_t)(t + 1) * kstep;
;             const char* a2 = last ? nA : cA + (size_t)(t + 2) * kstep; const char* b2 = last ? nB : cB + (size_t)(t + 2) * kstep;
;             const char* a3 = a2 + kstep; const char* b3 = b2 + kstep;
;             if constexpr (SP2) {
;             PG8_LDB(B0, 0, 0); PG8_LDB(B1, 0, 1); PG8_SCHED; PG8_LDA(At, 0, 0); PG8_STAGE(PG8_SA(1, 1), a1 + hstepA, voffA);
;             PG8_WAIT_V(8); PG8_WAIT_L(0); PG8_BAR; PG8_MMA(0, 0, At, B0); PG8_MMA(0, 1, At, B1); PG8_BAR; PG8_SCHED;
;             PG8_LDA(At, 0, 1); PG8_STAGE(PG8_SB(0, 0), b2, voffB); PG8_STAGE(PG8_SB(0, 1), b2 + hstepB, voffB); PG8_STAGE(PG8_SA(0, 0), a2, voffA);
;             PG8_WAIT_V(8); PG8_WAIT_L(0); PG8_BAR; PG8_MMA(1, 0, At, B0); PG8_MMA(1, 1, At, B1); PG8_BAR; PG8_SCHED;
.LBB0_804:
	ds_read_b128 v[144:147], v153
	ds_read_b128 v[156:159], v153 offset:1024
	ds_read_b128 v[160:163], v153 offset:2048
	ds_read_b128 v[164:167], v153 offset:3072
	ds_read_b128 v[168:171], v154
	ds_read_b128 v[172:175], v154 offset:1024
	ds_read_b128 v[176:179], v154 offset:2048
	ds_read_b128 v[180:183], v154 offset:3072
	s_add_u32 s22, s20, 0x100
	s_addc_u32 s23, s21, 0
	s_cmpk_eq_i32 s49, 0xa8
	s_cselect_b32 s27, s5, s23
	s_cselect_b32 s26, s4, s22
	s_cselect_b32 s25, s19, s48
	s_cselect_b32 s24, s18, s47
	v_lshl_add_u64 v[148:149], s[20:21], 0, v[136:137]
	s_add_i32 m0, s31, 0xc000
	ds_read_b128 v[184:187], v155
	ds_read_b128 v[188:191], v155 offset:1024
	ds_read_b128 v[192:195], v155 offset:2048
	ds_read_b128 v[196:199], v155 offset:3072
	ds_read_b128 v[200:203], v155 offset:4096
	ds_read_b128 v[204:207], v155 offset:5120
	ds_read_b128 v[208:211], v155 offset:6144
	ds_read_b128 v[212:215], v155 offset:7168
	global_load_lds_dwordx4 v[148:149], off
	v_lshl_add_u64 v[148:149], s[20:21], 0, v[138:139]
	s_add_i32 m0, s31, 0xe000
	s_nop 0
	global_load_lds_dwordx4 v[148:149], off
	s_waitcnt vmcnt(8) lgkmcnt(0)
	s_setprio 1
	s_barrier
	v_mfma_f32_16x16x32_bf16 v[124:127], v[144:147], v[184:187], v[124:127]
	v_mfma_f32_16x16x32_bf16 v[120:123], v[160:163], v[184:187], v[120:123]
	v_mfma_f32_16x16x32_bf16 v[108:111], v[144:147], v[192:195], v[108:111]
	v_mfma_f32_16x16x32_bf16 v[104:107], v[160:163], v[192:195], v[104:107]
	v_mfma_f32_16x16x32_bf16 v[92:95], v[144:147], v[200:203], v[92:95]
	v_mfma_f32_16x16x32_bf16 v[88:91], v[160:163], v[200:203], v[88:91]
	v_mfma_f32_16x16x32_bf16 v[76:79], v[144:147], v[208:211], v[76:79]
	v_mfma_f32_16x16x32_bf16 v[72:75], v[160:163], v[208:211], v[72:75]
	v_mfma_f32_16x16x32_bf16 v[124:127], v[156:159], v[188:191], v[124:127]
	v_mfma_f32_16x16x32_bf16 v[120:123], v[164:167], v[188:191], v[120:123]
	v_mfma_f32_16x16x32_bf16 v[108:111], v[156:159], v[196:199], v[108:111]
	v_mfma_f32_16x16x32_bf16 v[104:107], v[164:167], v[196:199], v[104:107]
	v_mfma_f32_16x16x32_bf16 v[92:95], v[156:159], v[204:207], v[92:95]
	v_mfma_f32_16x16x32_bf16 v[88:91], v[164:167], v[204:207], v[88:91]
	v_mfma_f32_16x16x32_bf16 v[76:79], v[156:159], v[212:215], v[76:79]
	v_mfma_f32_16x16x32_bf16 v[72:75], v[164:167], v[212:215], v[72:75]
	v_mfma_f32_16x16x32_bf16 v[116:119], v[168:171], v[184:187], v[116:119]
	v_mfma_f32_16x16x32_bf16 v[112:115], v[176:179], v[184:187], v[112:115]
	v_mfma_f32_16x16x32_bf16 v[100:103], v[168:171], v[192:195], v[100:103]
	v_mfma_f32_16x16x32_bf16 v[96:99], v[176:179], v[192:195], v[96:99]
	v_mfma_f32_16x16x32_bf16 v[84:87], v[168:171], v[200:203], v[84:87]
	v_mfma_f32_16x16x32_bf16 v[80:83], v[176:179], v[200:203], v[80:83]
	v_mfma_f32_16x16x32_bf16 v[68:71], v[168:171], v[208:211], v[68:71]
	v_mfma_f32_16x16x32_bf16 v[64:67], v[176:179], v[208:211], v[64:67]
	v_mfma_f32_16x16x32_bf16 v[116:119], v[172:175], v[188:191], v[116:119]
	v_mfma_f32_16x16x32_bf16 v[112:115], v[180:183], v[188:191], v[112:115]
	v_mfma_f32_16x16x32_bf16 v[100:103], v[172:175], v[196:199], v[100:103]
	v_mfma_f32_16x16x32_bf16 v[96:99], v[180:183], v[196:199], v[96:99]
	v_mfma_f32_16x16x32_bf16 v[84:87], v[172:175], v[204:207], v[84:87]
	v_mfma_f32_16x16x32_bf16 v[80:83], v[180:183], v[204:207], v[80:83]
	v_mfma_f32_16x16x32_bf16 v[68:71], v[172:175], v[212:215], v[68:71]
	v_mfma_f32_16x16x32_bf16 v[64:67], v[180:183], v[212:215], v[64:67]
	s_barrier
	s_setprio 0
	s_add_i32 s20, s40, s28
	v_lshl_add_u64 v[148:149], s[24:25], 0, v[130:131]
	s_mov_b32 m0, s20
	ds_read_b128 v[184:187], v155 offset:16384
	ds_read_b128 v[188:191], v155 offset:17408
	ds_read_b128 v[192:195], v155 offset:18432
	ds_read_b128 v[196:199], v155 offset:19456
	ds_read_b128 v[200:203], v155 offset:20480
	ds_read_b128 v[204:207], v155 offset:21504
	ds_read_b128 v[208:211], v155 offset:22528
	ds_read_b128 v[212:215], v155 offset:23552
	global_load_lds_dwordx4 v[148:149], off
	s_add_i32 m0, s20, 0x2000
	s_add_u32 s20, s24, 0x2b0000
	v_lshl_add_u64 v[216:217], s[24:25], 0, v[134:135]
	s_addc_u32 s21, s25, 0
	s_add_i32 s50, s41, s28
	global_load_lds_dwordx4 v[216:217], off
	v_lshl_add_u64 v[218:219], s[20:21], 0, v[130:131]
	s_mov_b32 m0, s50
	v_lshl_add_u64 v[220:221], s[26:27], 0, v[132:133]
	global_load_lds_dwordx4 v[218:219], off
	v_lshl_add_u64 v[218:219], s[20:21], 0, v[134:135]
	s_add_i32 m0, s50, 0x2000
	s_nop 0
	global_load_lds_dwordx4 v[218:219], off
	v_lshl_add_u64 v[218:219], s[26:27], 0, v[128:129]
	s_mov_b32 m0, s31
	s_nop 0
	global_load_lds_dwordx4 v[218:219], off
	s_mov_b32 m0, s33
	s_nop 0
	global_load_lds_dwordx4 v[220:221], off
	s_waitcnt vmcnt(8) lgkmcnt(0)
	s_setprio 1
	s_barrier
; #define PG8_STAGE(bufoff, gbase, voff) do { _Pragma("unroll") for (int _i = 0; _i < 2; ++_i) \
;         __builtin_amdgcn_global_load_lds((const unsigned*)((const char*)(gbase) + (voff)[_i]), (LAS unsigned*)(lds + (bufoff) + ldsw + _i * 8192), 16, 0, 0); } while (0)
; #define PG8_LDA(dst, b, h) do { _Pragma("unroll") for (int m = 0; m < 4; ++m) _Pragma("unroll") for (int k = 0; k < 2; ++k) dst[m][k] = *(const LAS bf16x8*)(lds + PG8_SA(b, h) + aoff + m * 2048 + k * 1024); } while (0)
; #define PG8_LDB(dst, b, h) do { _Pragma("unroll") for (int n = 0; n < 2; ++n) _Pragma("unroll") for (int k = 0; k < 2; ++k) dst[n][k] = *(const LAS bf16x8*)(lds + PG8_SB(b, h) + boff + n * 2048 + k * 1024); } while (0)
; #define PG8_MMA(ai, bj, At, Bt) do { __builtin_amdgcn_s_setprio(1); _Pragma("unroll") for (int m = 0; m < 4; ++m) _Pragma("unroll") for (int n = 0; n < 2; ++n) _Pragma("unroll") for (int k = 0; k < 2; ++k) \
;         acc[ai][bj][m][n] = __builtin_amdgcn_mfma_f32_16x16x32_bf16(Bt[n][k], At[m][k], acc[ai][bj][m][n], 0, 0, 0); __builtin_amdgcn_s_setprio(0); } while (0)
; #define PG8_WAIT_V(n) asm volatile("s_waitcnt vmcnt(" #n ")" ::: "memory")
; #define PG8_WAIT_L(n) asm volatile("s_waitcnt lgkmcnt(" #n ")" ::: "memory")
; #define PG8_BAR __builtin_amdgcn_s_barrier()
; #define PG8_SCHED __builtin_amdgcn_sched_barrier(0)
; template <class Epi, bool ALIGN_EPI, bool SP2 = PG8_SP2_DEFAULT>
; __device__ __forceinline__ void gemm_phase(LAS unsigned char* lds, const Gemm g, const StaticOrder& S, const Epi& E) {
;     ...
;             PG8_WAIT_V(8); PG8_WAIT_L(0); PG8_BAR; PG8_MMA(1, 0, At, B0); PG8_MMA(1, 1, At, B1); PG8_BAR; PG8_SCHED;
;             PG8_LDB(B0, 1, 0); PG8_LDB(B1, 1, 1); PG8_SCHED; PG8_LDA(At, 1, 0); PG8_STAGE(PG8_SA(0, 1), a2 + hstepA, voffA);
;             PG8_WAIT_V(8); PG8_WAIT_L(0); PG8_BAR; PG8_MMA(0, 0, At, B0); PG8_MMA(0, 1, At, B1); PG8_BAR; PG8_SCHED;
	v_mfma_f32_16x16x32_bf16 v[60:63], v[144:147], v[184:187], v[60:63]
	v_mfma_f32_16x16x32_bf16 v[56:59], v[160:163], v[184:187], v[56:59]
	v_mfma_f32_16x16x32_bf16 v[44:47], v[144:147], v[192:195], v[44:47]
	v_mfma_f32_16x16x32_bf16 v[40:43], v[160:163], v[192:195], v[40:43]
	v_mfma_f32_16x16x32_bf16 v[28:31], v[144:147], v[200:203], v[28:31]
	v_mfma_f32_16x16x32_bf16 v[24:27], v[160:163], v[200:203], v[24:27]
	v_mfma_f32_16x16x32_bf16 v[12:15], v[144:147], v[208:211], v[12:15]
	v_mfma_f32_16x16x32_bf16 v[8:11], v[160:163], v[208:211], v[8:11]
	v_mfma_f32_16x16x32_bf16 v[60:63], v[156:159], v[188:191], v[60:63]
	v_mfma_f32_16x16x32_bf16 v[56:59], v[164:167], v[188:191], v[56:59]
	v_mfma_f32_16x16x32_bf16 v[44:47], v[156:159], v[196:199], v[44:47]
	v_mfma_f32_16x16x32_bf16 v[40:43], v[164:167], v[196:199], v[40:43]
	v_mfma_f32_16x16x32_bf16 v[28:31], v[156:159], v[204:207], v[28:31]
	v_mfma_f32_16x16x32_bf16 v[24:27], v[164:167], v[204:207], v[24:27]
	v_mfma_f32_16x16x32_bf16 v[12:15], v[156:159], v[212:215], v[12:15]
	v_mfma_f32_16x16x32_bf16 v[8:11], v[164:167], v[212:215], v[8:11]
	v_mfma_f32_16x16x32_bf16 v[52:55], v[168:171], v[184:187], v[52:55]
	v_mfma_f32_16x16x32_bf16 v[48:51], v[176:179], v[184:187], v[48:51]
	v_mfma_f32_16x16x32_bf16 v[36:39], v[168:171], v[192:195], v[36:39]
	v_mfma_f32_16x16x32_bf16 v[32:35], v[176:179], v[192:195], v[32:35]
	v_mfma_f32_16x16x32_bf16 v[20:23], v[168:171], v[200:203], v[20:23]
	v_mfma_f32_16x16x32_bf16 v[16:19], v[176:179], v[200:203], v[16:19]
	v_mfma_f32_16x16x32_bf16 v[4:7], v[168:171], v[208:211], v[4:7]
	v_mfma_f32_16x16x32_bf16 v[0:3], v[176:179], v[208:211], v[0:3]
	v_mfma_f32_16x16x32_bf16 v[52:55], v[172:175], v[188:191], v[52:55]
	v_mfma_f32_16x16x32_bf16 v[48:51], v[180:183], v[188:191], v[48:51]
	v_mfma_f32_16x16x32_bf16 v[36:39], v[172:175], v[196:199], v[36:39]
	v_mfma_f32_16x16x32_bf16 v[32:35], v[180:183], v[196:199], v[32:35]
	v_mfma_f32_16x16x32_bf16 v[20:23], v[172:175], v[204:207], v[20:23]
	v_mfma_f32_16x16x32_bf16 v[16:19], v[180:183], v[204:207], v[16:19]
	v_mfma_f32_16x16x32_bf16 v[4:7], v[172:175], v[212:215], v[4:7]
	v_mfma_f32_16x16x32_bf16 v[0:3], v[180:183], v[212:215], v[0:3]
	s_barrier
	s_setprio 0
	s_add_i32 s50, 0, 0x18000
	s_add_i32 s51, 0, 0x1c000
	v_add_u32_e32 v164, s50, v151
	v_add_u32_e32 v180, s51, v151
	ds_read_b128 v[144:147], v164
	ds_read_b128 v[156:159], v164 offset:1024
	ds_read_b128 v[160:163], v164 offset:2048
	ds_read_b128 v[164:167], v164 offset:3072
	ds_read_b128 v[168:171], v180
	ds_read_b128 v[172:175], v180 offset:1024
	ds_read_b128 v[176:179], v180 offset:2048
	ds_read_b128 v[180:183], v180 offset:3072
	s_add_u32 s20, s26, 0x2b0000
	s_addc_u32 s21, s27, 0
	s_mov_b32 m0, s34
	v_lshl_add_u64 v[222:223], s[20:21], 0, v[128:129]
	ds_read_b128 v[184:187], v155 offset:32768
	ds_read_b128 v[188:191], v155 offset:33792
	ds_read_b128 v[192:195], v155 offset:34816
	ds_read_b128 v[196:199], v155 offset:35840
	ds_read_b128 v[200:203], v155 offset:36864
	ds_read_b128 v[204:207], v155 offset:37888
	ds_read_b128 v[208:211], v155 offset:38912
	ds_read_b128 v[212:215], v155 offset:39936
	global_load_lds_dwordx4 v[222:223], off
	v_lshl_add_u64 v[222:223], s[20:21], 0, v[132:133]
	s_mov_b32 m0, s35
	s_nop 0
	global_load_lds_dwordx4 v[222:223], off
	s_waitcnt vmcnt(8) lgkmcnt(0)
	s_setprio 1
	s_barrier
	v_mfma_f32_16x16x32_bf16 v[124:127], v[144:147], v[184:187], v[124:127]
	v_mfma_f32_16x16x32_bf16 v[120:123], v[160:163], v[184:187], v[120:123]
	v_mfma_f32_16x16x32_bf16 v[108:111], v[144:147], v[192:195], v[108:111]
	v_mfma_f32_16x16x32_bf16 v[104:107], v[160:163], v[192:195], v[104:107]
	v_mfma_f32_16x16x32_bf16 v[92:95], v[144:147], v[200:203], v[92:95]
	v_mfma_f32_16x16x32_bf16 v[88:91], v[160:163], v[200:203], v[88:91]
	v_mfma_f32_16x16x32_bf16 v[76:79], v[144:147], v[208:211], v[76:79]
	v_mfma_f32_16x16x32_bf16 v[72:75], v[160:163], v[208:211], v[72:75]
	v_mfma_f32_16x16x32_bf16 v[124:127], v[156:159], v[188:191], v[124:127]
	v_mfma_f32_16x16x32_bf16 v[120:123], v[164:167], v[188:191], v[120:123]
	v_mfma_f32_16x16x32_bf16 v[108:111], v[156:159], v[196:199], v[108:111]
	v_mfma_f32_16x16x32_bf16 v[104:107], v[164:167], v[196:199], v[104:107]
	v_mfma_f32_16x16x32_bf16 v[92:95], v[156:159], v[204:207], v[92:95]
	v_mfma_f32_16x16x32_bf16 v[88:91], v[164:167], v[204:207], v[88:91]
	v_mfma_f32_16x16x32_bf16 v[76:79], v[156:159], v[212:215], v[76:79]
	v_mfma_f32_16x16x32_bf16 v[72:75], v[164:167], v[212:215], v[72:75]
	v_mfma_f32_16x16x32_bf16 v[116:119], v[168:171], v[184:187], v[116:119]
	v_mfma_f32_16x16x32_bf16 v[112:115], v[176:179], v[184:187], v[112:115]
	v_mfma_f32_16x16x32_bf16 v[100:103], v[168:171], v[192:195], v[100:103]
	v_mfma_f32_16x16x32_bf16 v[96:99], v[176:179], v[192:195], v[96:99]
	v_mfma_f32_16x16x32_bf16 v[84:87], v[168:171], v[200:203], v[84:87]
	v_mfma_f32_16x16x32_bf16 v[80:83], v[176:179], v[200:203], v[80:83]
	v_mfma_f32_16x16x32_bf16 v[68:71], v[168:171], v[208:211], v[68:71]
	v_mfma_f32_16x16x32_bf16 v[64:67], v[176:179], v[208:211], v[64:67]
	v_mfma_f32_16x16x32_bf16 v[116:119], v[172:175], v[188:191], v[116:119]
	v_mfma_f32_16x16x32_bf16 v[112:115], v[180:183], v[188:191], v[112:115]
	v_mfma_f32_16x16x32_bf16 v[100:103], v[172:175], v[196:199], v[100:103]
	v_mfma_f32_16x16x32_bf16 v[96:99], v[180:183], v[196:199], v[96:99]
	v_mfma_f32_16x16x32_bf16 v[84:87], v[172:175], v[204:207], v[84:87]
	v_mfma_f32_16x16x32_bf16 v[80:83], v[180:183], v[204:207], v[80:83]
	v_mfma_f32_16x16x32_bf16 v[68:71], v[172:175], v[212:215], v[68:71]
	v_mfma_f32_16x16x32_bf16 v[64:67], v[180:183], v[212:215], v[64:67]
	s_barrier
; #define PG8_STAGE(bufoff, gbase, voff) do { _Pragma("unroll") for (int _i = 0; _i < 2; ++_i) \
;         __builtin_amdgcn_global_load_lds((const unsigned*)((const char*)(gbase) + (voff)[_i]), (LAS unsigned*)(lds + (bufoff) + ldsw + _i * 8192), 16, 0, 0); } while (0)
; #define PG8_LDA(dst, b, h) do { _Pragma("unroll") for (int m = 0; m < 4; ++m) _Pragma("unroll") for (int k = 0; k < 2; ++k) dst[m][k] = *(const LAS bf16x8*)(lds + PG8_SA(b, h) + aoff + m * 2048 + k * 1024); } while (0)
; #define PG8_MMA(ai, bj, At, Bt) do { __builtin_amdgcn_s_setprio(1); _Pragma("unroll") for (int m = 0; m < 4; ++m) _Pragma("unroll") for (int n = 0; n < 2; ++n) _Pragma("unroll") for (int k = 0; k < 2; ++k) \
;         acc[ai][bj][m][n] = __builtin_amdgcn_mfma_f32_16x16x32_bf16(Bt[n][k], At[m][k], acc[ai][bj][m][n], 0, 0, 0); __builtin_amdgcn_s_setprio(0); } while (0)
; #define PG8_WAIT_V(n) asm volatile("s_waitcnt vmcnt(" #n ")" ::: "memory")
; #define PG8_WAIT_L(n) asm volatile("s_waitcnt lgkmcnt(" #n ")" ::: "memory")
; #define PG8_BAR __builtin_amdgcn_s_barrier()
; #define PG8_SCHED __builtin_amdgcn_sched_barrier(0)
; template <class Epi, bool ALIGN_EPI, bool SP2 = PG8_SP2_DEFAULT>
; __device__ __forceinline__ void gemm_phase(LAS unsigned char* lds, const Gemm g, const StaticOrder& S, const Epi& E) {
;     ...
;             PG8_LDA(At, 1, 1); PG8_STAGE(PG8_SB(1, 0), b3, voffB); PG8_STAGE(PG8_SB(1, 1), b3 + hstepB, voffB); PG8_STAGE(PG8_SA(1, 0), a3, voffA);
;             PG8_WAIT_V(8); PG8_WAIT_L(0); PG8_BAR; PG8_MMA(1, 0, At, B0); PG8_MMA(1, 1, At, B1); PG8_BAR; PG8_SCHED;
;     ...
;         if constexpr (ALIGN_EPI) { if (wr == 0) PG8_BAR; }
	s_setprio 0
	s_add_i32 s20, s50, s28
	v_lshl_add_u64 v[148:149], v[148:149], 0, s[6:7]
	s_mov_b32 m0, s20
	ds_read_b128 v[184:187], v155 offset:49152
	ds_read_b128 v[188:191], v155 offset:50176
	ds_read_b128 v[192:195], v155 offset:51200
	ds_read_b128 v[196:199], v155 offset:52224
	ds_read_b128 v[200:203], v155 offset:53248
	ds_read_b128 v[204:207], v155 offset:54272
	ds_read_b128 v[208:211], v155 offset:55296
	ds_read_b128 v[212:215], v155 offset:56320
	global_load_lds_dwordx4 v[148:149], off
	s_add_i32 m0, s20, 0x2000
	s_add_u32 s20, s24, 0x2b0080
	v_lshl_add_u64 v[148:149], v[216:217], 0, s[6:7]
	s_addc_u32 s21, s25, 0
	s_add_i32 s24, s51, s28
	global_load_lds_dwordx4 v[148:149], off
	v_lshl_add_u64 v[148:149], s[20:21], 0, v[130:131]
	s_mov_b32 m0, s24
	s_nop 0
	global_load_lds_dwordx4 v[148:149], off
	v_lshl_add_u64 v[148:149], s[20:21], 0, v[134:135]
	s_add_i32 m0, s24, 0x2000
	s_nop 0
	global_load_lds_dwordx4 v[148:149], off
	v_lshl_add_u64 v[148:149], v[218:219], 0, s[6:7]
	s_mov_b32 m0, s37
	s_nop 0
	global_load_lds_dwordx4 v[148:149], off
	v_lshl_add_u64 v[148:149], v[220:221], 0, s[6:7]
	s_mov_b32 m0, s38
	s_nop 0
	global_load_lds_dwordx4 v[148:149], off
	s_waitcnt vmcnt(8) lgkmcnt(0)
	s_setprio 1
	s_barrier
	v_mfma_f32_16x16x32_bf16 v[60:63], v[144:147], v[184:187], v[60:63]
	v_mfma_f32_16x16x32_bf16 v[56:59], v[160:163], v[184:187], v[56:59]
	v_mfma_f32_16x16x32_bf16 v[44:47], v[144:147], v[192:195], v[44:47]
	v_mfma_f32_16x16x32_bf16 v[40:43], v[160:163], v[192:195], v[40:43]
	v_mfma_f32_16x16x32_bf16 v[28:31], v[144:147], v[200:203], v[28:31]
	v_mfma_f32_16x16x32_bf16 v[24:27], v[160:163], v[200:203], v[24:27]
	v_mfma_f32_16x16x32_bf16 v[12:15], v[144:147], v[208:211], v[12:15]
	v_mfma_f32_16x16x32_bf16 v[8:11], v[160:163], v[208:211], v[8:11]
	v_mfma_f32_16x16x32_bf16 v[60:63], v[156:159], v[188:191], v[60:63]
	v_mfma_f32_16x16x32_bf16 v[56:59], v[164:167], v[188:191], v[56:59]
	v_mfma_f32_16x16x32_bf16 v[44:47], v[156:159], v[196:199], v[44:47]
	v_mfma_f32_16x16x32_bf16 v[40:43], v[164:167], v[196:199], v[40:43]
	v_mfma_f32_16x16x32_bf16 v[28:31], v[156:159], v[204:207], v[28:31]
	v_mfma_f32_16x16x32_bf16 v[24:27], v[164:167], v[204:207], v[24:27]
	v_mfma_f32_16x16x32_bf16 v[12:15], v[156:159], v[212:215], v[12:15]
	v_mfma_f32_16x16x32_bf16 v[8:11], v[164:167], v[212:215], v[8:11]
	v_mfma_f32_16x16x32_bf16 v[52:55], v[168:171], v[184:187], v[52:55]
	v_mfma_f32_16x16x32_bf16 v[48:51], v[176:179], v[184:187], v[48:51]
	v_mfma_f32_16x16x32_bf16 v[36:39], v[168:171], v[192:195], v[36:39]
	v_mfma_f32_16x16x32_bf16 v[32:35], v[176:179], v[192:195], v[32:35]
	v_mfma_f32_16x16x32_bf16 v[20:23], v[168:171], v[200:203], v[20:23]
	v_mfma_f32_16x16x32_bf16 v[16:19], v[176:179], v[200:203], v[16:19]
	v_mfma_f32_16x16x32_bf16 v[4:7], v[168:171], v[208:211], v[4:7]
	v_mfma_f32_16x16x32_bf16 v[0:3], v[176:179], v[208:211], v[0:3]
	v_mfma_f32_16x16x32_bf16 v[52:55], v[172:175], v[188:191], v[52:55]
	v_mfma_f32_16x16x32_bf16 v[48:51], v[180:183], v[188:191], v[48:51]
	v_mfma_f32_16x16x32_bf16 v[36:39], v[172:175], v[196:199], v[36:39]
	v_mfma_f32_16x16x32_bf16 v[32:35], v[180:183], v[196:199], v[32:35]
	v_mfma_f32_16x16x32_bf16 v[20:23], v[172:175], v[204:207], v[20:23]
	v_mfma_f32_16x16x32_bf16 v[16:19], v[180:183], v[204:207], v[16:19]
	v_mfma_f32_16x16x32_bf16 v[4:7], v[172:175], v[212:215], v[4:7]
	v_mfma_f32_16x16x32_bf16 v[0:3], v[180:183], v[212:215], v[0:3]
	s_barrier
	s_setprio 0
	s_add_i32 s49, s49, 2
	s_add_u32 s47, s47, 0x100
	s_addc_u32 s48, s48, 0
	s_cmpk_gt_u32 s49, 0xa9
	s_mov_b64 s[20:21], s[22:23]
	s_cbranch_scc0 .LBB0_804
	s_and_b64 vcc, exec, s[8:9]
	s_cbranch_vccz .LBB0_807
	s_barrier
